# GEMM tile-top wait relaxed to vmcnt(16) (prefetch older than the epilogue stores), first-tile path keeps vmcnt(0); compute-dtype comment added
# baseline (speedup 1.0000x reference)
.LBB0_70:
	v_readfirstlane_b32 s5, v178
	s_lshr_b32 s4, s5, 6
	s_lshl_b32 s14, s4, 5
	s_lshl_b64 s[2:3], s[14:15], 10
	s_lshl_b32 s8, s4, 12
	s_mov_b64 s[6:7], -1
	s_and_b64 vcc, exec, s[96:97]
	s_cbranch_vccz .LBB0_72
	s_lshl_b64 s[6:7], s[2:3], 1
	s_add_u32 s10, s90, s6
	s_addc_u32 s11, s91, s7
	s_add_u32 s6, s78, s6
	s_addc_u32 s7, s79, s7
	s_add_i32 s0, s8, 0
	v_mov_b32_e32 v139, v129
	s_mov_b32 m0, s0
	v_mov_b32_e32 v141, v129
	v_lshl_add_u64 v[0:1], s[6:7], 0, v[138:139]
	global_load_lds_dwordx4 v138, s[6:7]
	s_add_i32 m0, s0, 0x8000
	v_lshl_add_u64 v[4:5], s[6:7], 0, v[140:141]
	s_mov_b64 s[6:7], 0x4000
	global_load_lds_dwordx4 v138, s[10:11]
	v_lshl_add_u64 v[6:7], v[4:5], 0, s[6:7]
	s_add_i32 m0, s0, 0x400
	v_lshl_add_u64 v[2:3], s[10:11], 0, v[138:139]
	global_load_lds_dwordx4 v[6:7], off
	v_lshl_add_u64 v[6:7], s[10:11], 0, v[140:141]
	v_lshl_add_u64 v[8:9], v[6:7], 0, s[6:7]
	s_add_i32 m0, s0, 0x8400
	s_mov_b64 s[6:7], 0x8000
	global_load_lds_dwordx4 v[8:9], off
	v_lshl_add_u64 v[0:1], v[0:1], 0, s[6:7]
	s_add_i32 m0, s0, 0x800
	s_or_b32 s11, s8, 0x400
	global_load_lds_dwordx4 v[0:1], off
	v_lshl_add_u64 v[0:1], v[2:3], 0, s[6:7]
	s_add_i32 m0, s0, 0x8800
	s_mov_b64 s[6:7], 0xc000
	global_load_lds_dwordx4 v[0:1], off
	v_lshl_add_u64 v[0:1], v[4:5], 0, s[6:7]
	s_add_i32 m0, s0, 0xc00
	s_or_b32 s10, s8, 0x800
	global_load_lds_dwordx4 v[0:1], off
	v_lshl_add_u64 v[0:1], v[6:7], 0, s[6:7]
	s_add_i32 m0, s0, 0x8c00
	s_or_b32 s9, s8, 0xc00
	global_load_lds_dwordx4 v[0:1], off
	s_waitcnt vmcnt(0)
	s_mov_b64 s[6:7], 0

.LBB0_74:
	s_lshr_b32 s0, s5, 1
	s_and_b32 s0, s0, 0x1ffff80
	v_or_b32_e32 v0, s0, v154
	s_and_b32 s0, s5, 0xc0
	s_mov_b32 s5, s15
	s_lshl_b64 s[4:5], s[4:5], 16
	v_lshlrev_b32_e32 v128, 7, v0
	v_or_b32_e32 v0, s0, v154
	s_add_u32 s6, s4, s74
	v_lshlrev_b32_e32 v139, 7, v0
	v_lshl_add_u64 v[0:1], s[66:67], 0, v[130:131]
	s_addc_u32 s7, s5, s75
	s_waitcnt vmcnt(16)
	v_lshl_add_u64 v[142:143], v[0:1], 0, s[6:7]
	s_add_u32 s4, s4, s76
	v_lshl_add_u64 v[0:1], s[66:67], 0, v[134:135]
	s_addc_u32 s5, s5, s77
	v_lshl_add_u64 v[146:147], v[0:1], 0, s[6:7]
	v_mov_b32_e32 v0, 0
	v_lshl_add_u64 v[144:145], v[132:133], 0, s[4:5]
	v_lshl_add_u64 v[148:149], v[136:137], 0, s[4:5]
	s_mov_b64 s[4:5], 0
	s_mov_b32 s12, 0
	v_mov_b32_e32 v1, v0
	v_mov_b32_e32 v2, v0
	v_mov_b32_e32 v3, v0
	v_mov_b32_e32 v4, v0
	v_mov_b32_e32 v5, v0
	v_mov_b32_e32 v6, v0
	v_mov_b32_e32 v7, v0
	v_mov_b32_e32 v8, v0
	v_mov_b32_e32 v9, v0
	v_mov_b32_e32 v10, v0
	v_mov_b32_e32 v11, v0
	v_mov_b32_e32 v12, v0
	v_mov_b32_e32 v13, v0
	v_mov_b32_e32 v14, v0
	v_mov_b32_e32 v15, v0
	v_mov_b32_e32 v16, v0
	v_mov_b32_e32 v17, v0
	v_mov_b32_e32 v18, v0
	v_mov_b32_e32 v19, v0
	v_mov_b32_e32 v20, v0
	v_mov_b32_e32 v21, v0
	v_mov_b32_e32 v22, v0
	v_mov_b32_e32 v23, v0
	v_mov_b32_e32 v24, v0
	v_mov_b32_e32 v25, v0
	v_mov_b32_e32 v26, v0
	v_mov_b32_e32 v27, v0
	v_mov_b32_e32 v28, v0
	v_mov_b32_e32 v29, v0
	v_mov_b32_e32 v30, v0
	v_mov_b32_e32 v31, v0
	v_mov_b32_e32 v32, v0
	v_mov_b32_e32 v33, v0
	v_mov_b32_e32 v34, v0
	v_mov_b32_e32 v35, v0
	v_mov_b32_e32 v36, v0
	v_mov_b32_e32 v37, v0
	v_mov_b32_e32 v38, v0
	v_mov_b32_e32 v39, v0
	v_mov_b32_e32 v40, v0
	v_mov_b32_e32 v41, v0
	v_mov_b32_e32 v42, v0
	v_mov_b32_e32 v43, v0
	v_mov_b32_e32 v44, v0
	v_mov_b32_e32 v45, v0
	v_mov_b32_e32 v46, v0
	v_mov_b32_e32 v47, v0
	v_mov_b32_e32 v48, v0
	v_mov_b32_e32 v49, v0
	v_mov_b32_e32 v50, v0
	v_mov_b32_e32 v51, v0
	v_mov_b32_e32 v52, v0
	v_mov_b32_e32 v53, v0
	v_mov_b32_e32 v54, v0
	v_mov_b32_e32 v55, v0
	v_mov_b32_e32 v56, v0
	v_mov_b32_e32 v57, v0
	v_mov_b32_e32 v58, v0
	v_mov_b32_e32 v59, v0
	v_mov_b32_e32 v60, v0
	v_mov_b32_e32 v61, v0
	v_mov_b32_e32 v62, v0
	v_mov_b32_e32 v63, v0
	v_mov_b32_e32 v64, v0
	v_mov_b32_e32 v65, v0
	v_mov_b32_e32 v66, v0
	v_mov_b32_e32 v67, v0
	v_mov_b32_e32 v68, v0
	v_mov_b32_e32 v69, v0
	v_mov_b32_e32 v70, v0
	v_mov_b32_e32 v71, v0
	v_mov_b32_e32 v72, v0
	v_mov_b32_e32 v73, v0
	v_mov_b32_e32 v74, v0
	v_mov_b32_e32 v75, v0
	v_mov_b32_e32 v76, v0
	v_mov_b32_e32 v77, v0
	v_mov_b32_e32 v78, v0
	v_mov_b32_e32 v79, v0
	v_mov_b32_e32 v80, v0
	v_mov_b32_e32 v81, v0
	v_mov_b32_e32 v82, v0
	v_mov_b32_e32 v83, v0
	v_mov_b32_e32 v84, v0
	v_mov_b32_e32 v85, v0
	v_mov_b32_e32 v86, v0
	v_mov_b32_e32 v87, v0
	v_mov_b32_e32 v88, v0
	v_mov_b32_e32 v89, v0
	v_mov_b32_e32 v90, v0
	v_mov_b32_e32 v91, v0
	v_mov_b32_e32 v92, v0
	v_mov_b32_e32 v93, v0
	v_mov_b32_e32 v94, v0
	v_mov_b32_e32 v95, v0
	v_mov_b32_e32 v96, v0
	v_mov_b32_e32 v97, v0
	v_mov_b32_e32 v98, v0
	v_mov_b32_e32 v99, v0
	v_mov_b32_e32 v100, v0
	v_mov_b32_e32 v101, v0
	v_mov_b32_e32 v102, v0
	v_mov_b32_e32 v103, v0
	v_mov_b32_e32 v104, v0
	v_mov_b32_e32 v105, v0
	v_mov_b32_e32 v106, v0
	v_mov_b32_e32 v107, v0
	v_mov_b32_e32 v108, v0
	v_mov_b32_e32 v109, v0
	v_mov_b32_e32 v110, v0
	v_mov_b32_e32 v111, v0
	v_mov_b32_e32 v112, v0
	v_mov_b32_e32 v113, v0
	v_mov_b32_e32 v114, v0
	v_mov_b32_e32 v115, v0
	v_mov_b32_e32 v116, v0
	v_mov_b32_e32 v117, v0
	v_mov_b32_e32 v118, v0
	v_mov_b32_e32 v119, v0
	v_mov_b32_e32 v120, v0
	v_mov_b32_e32 v121, v0
	v_mov_b32_e32 v122, v0
	v_mov_b32_e32 v123, v0
	v_mov_b32_e32 v124, v0
	v_mov_b32_e32 v125, v0
	v_mov_b32_e32 v126, v0
	v_mov_b32_e32 v127, v0
	s_waitcnt vmcnt(16) lgkmcnt(0)
	s_barrier
	v_bfe_u32 v250, v178, 3, 3
	v_and_b32_e32 v251, 7, v178
	v_lshrrev_b32_e32 v252, 1, v250
	v_xor_b32_e32 v251, v251, v252
	v_lshlrev_b32_e32 v251, 4, v251
	v_lshl_or_b32 v250, v250, 11, v251
	v_xor_b32_e32 v251, 64, v250
	v_add_u32_e32 v251, 0x4000, v251
	v_add_u32_e32 v252, 0x8000, v250
	v_add_u32_e32 v253, 0x8000, v251
	v_lshl_add_u64 v[242:243], v[142:143], 0, s[4:5]
	v_lshl_add_u64 v[242:243], v[242:243], 0, s[38:39]
	v_lshl_add_u64 v[244:245], v[144:145], 0, s[4:5]
	v_lshl_add_u64 v[244:245], v[244:245], 0, s[40:41]
	v_add_u32_e32 v254, v128, v155
	v_add_u32_e32 v255, v139, v155
	v_readfirstlane_b32 s98, v242
	v_readfirstlane_b32 s99, v243
	v_readfirstlane_b32 s100, v244
	v_readfirstlane_b32 s101, v245
	ds_read_b128 v[206:209], v254
	ds_read_b128 v[210:213], v254 offset:2048
	ds_read_b128 v[150:153], v255 offset:32768
	ds_read_b128 v[194:197], v255 offset:34816
	ds_read_b128 v[198:201], v255 offset:36864
	ds_read_b128 v[202:205], v255 offset:38912
	s_nop 4
	s_lshl_b32 m0, s4, 9
	s_and_b32 m0, m0, 0x10000
	s_xor_b32 m0, m0, 0x10000
	s_add_i32 m0, m0, s8
	s_nop 0
	global_load_lds_dwordx4 v250, s[98:99]
	s_add_i32 m0, m0, 0x8000
	s_nop 0
	global_load_lds_dwordx4 v250, s[100:101]
	s_add_i32 m0, m0, 0xffff8400
	s_nop 0
	global_load_lds_dwordx4 v251, s[98:99]
	s_add_i32 m0, m0, 0x8000
	s_nop 0
	global_load_lds_dwordx4 v251, s[100:101]

.LBB0_531:
	s_lshr_b32 s0, s5, 1
	s_and_b32 s0, s0, 0x1ffff80
	v_or_b32_e32 v0, s0, v154
	s_and_b32 s0, s5, 0xc0
	s_mov_b32 s5, s15
	s_lshl_b64 s[4:5], s[4:5], 16
	v_lshlrev_b32_e32 v139, 7, v0
	v_or_b32_e32 v0, s0, v154
	s_add_u32 s12, s4, s74
	v_lshlrev_b32_e32 v128, 7, v0
	v_lshl_add_u64 v[0:1], s[66:67], 0, v[130:131]
	s_addc_u32 s13, s5, s75
	s_waitcnt vmcnt(16)
	v_lshl_add_u64 v[142:143], v[0:1], 0, s[12:13]
	s_add_u32 s6, s4, s76
	v_lshl_add_u64 v[0:1], s[66:67], 0, v[134:135]
	s_addc_u32 s7, s5, s77
	v_lshl_add_u64 v[144:145], v[0:1], 0, s[12:13]
	v_mov_b32_e32 v0, 0
	s_mov_b32 s12, 0
	s_mov_b64 s[4:5], 0
	v_mov_b32_e32 v1, v0
	v_mov_b32_e32 v2, v0
	v_mov_b32_e32 v3, v0
	v_mov_b32_e32 v4, v0
	v_mov_b32_e32 v5, v0
	v_mov_b32_e32 v6, v0
	v_mov_b32_e32 v7, v0
	v_mov_b32_e32 v8, v0
	v_mov_b32_e32 v9, v0
	v_mov_b32_e32 v10, v0
	v_mov_b32_e32 v11, v0
	v_mov_b32_e32 v12, v0
	v_mov_b32_e32 v13, v0
	v_mov_b32_e32 v14, v0
	v_mov_b32_e32 v15, v0
	v_mov_b32_e32 v16, v0
	v_mov_b32_e32 v17, v0
	v_mov_b32_e32 v18, v0
	v_mov_b32_e32 v19, v0
	v_mov_b32_e32 v20, v0
	v_mov_b32_e32 v21, v0
	v_mov_b32_e32 v22, v0
	v_mov_b32_e32 v23, v0
	v_mov_b32_e32 v24, v0
	v_mov_b32_e32 v25, v0
	v_mov_b32_e32 v26, v0
	v_mov_b32_e32 v27, v0
	v_mov_b32_e32 v28, v0
	v_mov_b32_e32 v29, v0
	v_mov_b32_e32 v30, v0
	v_mov_b32_e32 v31, v0
	v_mov_b32_e32 v32, v0
	v_mov_b32_e32 v33, v0
	v_mov_b32_e32 v34, v0
	v_mov_b32_e32 v35, v0
	v_mov_b32_e32 v36, v0
	v_mov_b32_e32 v37, v0
	v_mov_b32_e32 v38, v0
	v_mov_b32_e32 v39, v0
	v_mov_b32_e32 v40, v0
	v_mov_b32_e32 v41, v0
	v_mov_b32_e32 v42, v0
	v_mov_b32_e32 v43, v0
	v_mov_b32_e32 v44, v0
	v_mov_b32_e32 v45, v0
	v_mov_b32_e32 v46, v0
	v_mov_b32_e32 v47, v0
	v_mov_b32_e32 v48, v0
	v_mov_b32_e32 v49, v0
	v_mov_b32_e32 v50, v0
	v_mov_b32_e32 v51, v0
	v_mov_b32_e32 v52, v0
	v_mov_b32_e32 v53, v0
	v_mov_b32_e32 v54, v0
	v_mov_b32_e32 v55, v0
	v_mov_b32_e32 v56, v0
	v_mov_b32_e32 v57, v0
	v_mov_b32_e32 v58, v0
	v_mov_b32_e32 v59, v0
	v_mov_b32_e32 v60, v0
	v_mov_b32_e32 v61, v0
	v_mov_b32_e32 v62, v0
	v_mov_b32_e32 v63, v0
	v_mov_b32_e32 v64, v0
	v_mov_b32_e32 v65, v0
	v_mov_b32_e32 v66, v0
	v_mov_b32_e32 v67, v0
	v_mov_b32_e32 v68, v0
	v_mov_b32_e32 v69, v0
	v_mov_b32_e32 v70, v0
	v_mov_b32_e32 v71, v0
	v_mov_b32_e32 v72, v0
	v_mov_b32_e32 v73, v0
	v_mov_b32_e32 v74, v0
	v_mov_b32_e32 v75, v0
	v_mov_b32_e32 v76, v0
	v_mov_b32_e32 v77, v0
	v_mov_b32_e32 v78, v0
	v_mov_b32_e32 v79, v0
	v_mov_b32_e32 v80, v0
	v_mov_b32_e32 v81, v0
	v_mov_b32_e32 v82, v0
	v_mov_b32_e32 v83, v0
	v_mov_b32_e32 v84, v0
	v_mov_b32_e32 v85, v0
	v_mov_b32_e32 v86, v0
	v_mov_b32_e32 v87, v0
	v_mov_b32_e32 v88, v0
	v_mov_b32_e32 v89, v0
	v_mov_b32_e32 v90, v0
	v_mov_b32_e32 v91, v0
	v_mov_b32_e32 v92, v0
	v_mov_b32_e32 v93, v0
	v_mov_b32_e32 v94, v0
	v_mov_b32_e32 v95, v0
	v_mov_b32_e32 v96, v0
	v_mov_b32_e32 v97, v0
	v_mov_b32_e32 v98, v0
	v_mov_b32_e32 v99, v0
	v_mov_b32_e32 v100, v0
	v_mov_b32_e32 v101, v0
	v_mov_b32_e32 v102, v0
	v_mov_b32_e32 v103, v0
	v_mov_b32_e32 v104, v0
	v_mov_b32_e32 v105, v0
	v_mov_b32_e32 v106, v0
	v_mov_b32_e32 v107, v0
	v_mov_b32_e32 v108, v0
	v_mov_b32_e32 v109, v0
	v_mov_b32_e32 v110, v0
	v_mov_b32_e32 v111, v0
	v_mov_b32_e32 v112, v0
	v_mov_b32_e32 v113, v0
	v_mov_b32_e32 v114, v0
	v_mov_b32_e32 v115, v0
	v_mov_b32_e32 v116, v0
	v_mov_b32_e32 v117, v0
	v_mov_b32_e32 v118, v0
	v_mov_b32_e32 v119, v0
	v_mov_b32_e32 v120, v0
	v_mov_b32_e32 v121, v0
	v_mov_b32_e32 v122, v0
	v_mov_b32_e32 v123, v0
	v_mov_b32_e32 v124, v0
	v_mov_b32_e32 v125, v0
	v_mov_b32_e32 v126, v0
	v_mov_b32_e32 v127, v0
	v_lshl_add_u64 v[146:147], v[132:133], 0, s[6:7]
	v_lshl_add_u64 v[148:149], v[136:137], 0, s[6:7]
	s_waitcnt vmcnt(16) lgkmcnt(0)
	s_barrier
	v_bfe_u32 v250, v178, 3, 3
	v_and_b32_e32 v251, 7, v178
	v_lshrrev_b32_e32 v252, 1, v250
	v_xor_b32_e32 v251, v251, v252
	v_lshlrev_b32_e32 v251, 4, v251
	v_lshl_or_b32 v250, v250, 11, v251
	v_xor_b32_e32 v251, 64, v250
	v_add_u32_e32 v251, 0x4000, v251
	v_add_u32_e32 v252, 0x8000, v250
	v_add_u32_e32 v253, 0x8000, v251
	v_lshl_add_u64 v[242:243], v[142:143], 0, s[4:5]
	v_lshl_add_u64 v[242:243], v[242:243], 0, s[38:39]
	v_lshl_add_u64 v[244:245], v[146:147], 0, s[4:5]
	v_lshl_add_u64 v[244:245], v[244:245], 0, s[40:41]
	v_add_u32_e32 v254, v139, v155
	v_add_u32_e32 v255, v128, v155
	v_readfirstlane_b32 s98, v242
	v_readfirstlane_b32 s99, v243
	v_readfirstlane_b32 s100, v244
	v_readfirstlane_b32 s101, v245
	ds_read_b128 v[206:209], v254
	ds_read_b128 v[210:213], v254 offset:2048
	ds_read_b128 v[150:153], v255 offset:32768
	ds_read_b128 v[194:197], v255 offset:34816
	ds_read_b128 v[198:201], v255 offset:36864
	ds_read_b128 v[202:205], v255 offset:38912
	s_nop 4
	s_lshl_b32 m0, s4, 9
	s_and_b32 m0, m0, 0x10000
	s_xor_b32 m0, m0, 0x10000
	s_add_i32 m0, m0, s8
	s_nop 0
	global_load_lds_dwordx4 v250, s[98:99]
	s_add_i32 m0, m0, 0x8000
	s_nop 0
	global_load_lds_dwordx4 v250, s[100:101]
	s_add_i32 m0, m0, 0xffff8400
	s_nop 0
	global_load_lds_dwordx4 v251, s[98:99]
	s_add_i32 m0, m0, 0x8000
	s_nop 0
	global_load_lds_dwordx4 v251, s[100:101]

.LBB0_731:
	v_readfirstlane_b32 s37, v178
	s_lshr_b32 s36, s37, 6
	s_xor_b64 s[52:53], s[26:27], -1
	s_lshl_b32 s2, s36, 5
	s_lshl_b64 s[26:27], s[2:3], 10
	s_lshl_b32 s2, s36, 12
	s_mov_b64 s[40:41], -1
	s_and_b64 vcc, exec, s[52:53]
	s_cbranch_vccz .LBB0_733
	s_add_u32 s19, s44, s34
	s_addc_u32 s53, s45, s35
	s_lshl_b64 s[40:41], s[26:27], 1
	s_add_u32 s52, s19, s40
	s_addc_u32 s53, s53, s41
	s_add_u32 s38, s38, s40
	s_addc_u32 s39, s39, s41
	s_add_i32 s19, s2, 0
	s_mov_b32 m0, s19
	v_mov_b32_e32 v139, v129
	global_load_lds_dwordx4 v128, s[38:39]
	s_add_i32 m0, s19, 0x8000
	v_lshl_add_u64 v[4:5], s[38:39], 0, v[138:139]
	global_load_lds_dwordx4 v128, s[52:53]
	v_lshl_add_u64 v[6:7], v[4:5], 0, s[4:5]
	s_add_i32 m0, s19, 0x400
	v_lshl_add_u64 v[0:1], s[38:39], 0, v[128:129]
	global_load_lds_dwordx4 v[6:7], off
	v_lshl_add_u64 v[6:7], s[52:53], 0, v[138:139]
	v_lshl_add_u64 v[8:9], v[6:7], 0, s[4:5]
	s_add_i32 m0, s19, 0x8400
	v_lshl_add_u64 v[2:3], s[52:53], 0, v[128:129]
	global_load_lds_dwordx4 v[8:9], off
	v_lshl_add_u64 v[0:1], v[0:1], 0, s[6:7]
	s_add_i32 m0, s19, 0x800
	s_or_b32 s53, s2, 0x400
	global_load_lds_dwordx4 v[0:1], off
	v_lshl_add_u64 v[0:1], v[2:3], 0, s[6:7]
	s_add_i32 m0, s19, 0x8800
	s_or_b32 s52, s2, 0x800
	global_load_lds_dwordx4 v[0:1], off
	v_lshl_add_u64 v[0:1], v[4:5], 0, s[8:9]
	s_add_i32 m0, s19, 0xc00
	s_mov_b64 s[40:41], 0
	global_load_lds_dwordx4 v[0:1], off
	v_lshl_add_u64 v[0:1], v[6:7], 0, s[8:9]
	s_add_i32 m0, s19, 0x8c00
	s_or_b32 s19, s2, 0xc00
	global_load_lds_dwordx4 v[0:1], off
	s_waitcnt vmcnt(0)

.LBB0_735:
	s_lshr_b32 s38, s37, 1
	s_and_b32 s38, s38, 0x1ffff80
	v_or_b32_e32 v0, s38, v148
	s_and_b32 s37, s37, 0xc0
	v_lshlrev_b32_e32 v139, 7, v0
	v_or_b32_e32 v0, s37, v148
	s_mov_b32 s37, s3
	s_lshl_b64 s[36:37], s[36:37], 16
	s_add_u32 s30, s36, s30
	v_lshlrev_b32_e32 v153, 7, v0
	v_lshl_add_u64 v[0:1], s[28:29], 0, v[130:131]
	s_addc_u32 s31, s37, s31
	s_waitcnt vmcnt(16)
	v_lshl_add_u64 v[140:141], v[0:1], 0, s[30:31]
	s_add_u32 s34, s36, s34
	v_lshl_add_u64 v[0:1], s[28:29], 0, v[134:135]
	s_addc_u32 s35, s37, s35
	v_lshl_add_u64 v[144:145], v[0:1], 0, s[30:31]
	v_mov_b32_e32 v0, 0
	v_lshl_add_u64 v[142:143], v[132:133], 0, s[34:35]
	v_lshl_add_u64 v[146:147], v[136:137], 0, s[34:35]
	s_mov_b64 s[28:29], 0
	s_mov_b32 s34, 0
	v_mov_b32_e32 v1, v0
	v_mov_b32_e32 v2, v0
	v_mov_b32_e32 v3, v0
	v_mov_b32_e32 v4, v0
	v_mov_b32_e32 v5, v0
	v_mov_b32_e32 v6, v0
	v_mov_b32_e32 v7, v0
	v_mov_b32_e32 v8, v0
	v_mov_b32_e32 v9, v0
	v_mov_b32_e32 v10, v0
	v_mov_b32_e32 v11, v0
	v_mov_b32_e32 v12, v0
	v_mov_b32_e32 v13, v0
	v_mov_b32_e32 v14, v0
	v_mov_b32_e32 v15, v0
	v_mov_b32_e32 v16, v0
	v_mov_b32_e32 v17, v0
	v_mov_b32_e32 v18, v0
	v_mov_b32_e32 v19, v0
	v_mov_b32_e32 v20, v0
	v_mov_b32_e32 v21, v0
	v_mov_b32_e32 v22, v0
	v_mov_b32_e32 v23, v0
	v_mov_b32_e32 v24, v0
	v_mov_b32_e32 v25, v0
	v_mov_b32_e32 v26, v0
	v_mov_b32_e32 v27, v0
	v_mov_b32_e32 v28, v0
	v_mov_b32_e32 v29, v0
	v_mov_b32_e32 v30, v0
	v_mov_b32_e32 v31, v0
	v_mov_b32_e32 v32, v0
	v_mov_b32_e32 v33, v0
	v_mov_b32_e32 v34, v0
	v_mov_b32_e32 v35, v0
	v_mov_b32_e32 v36, v0
	v_mov_b32_e32 v37, v0
	v_mov_b32_e32 v38, v0
	v_mov_b32_e32 v39, v0
	v_mov_b32_e32 v40, v0
	v_mov_b32_e32 v41, v0
	v_mov_b32_e32 v42, v0
	v_mov_b32_e32 v43, v0
	v_mov_b32_e32 v44, v0
	v_mov_b32_e32 v45, v0
	v_mov_b32_e32 v46, v0
	v_mov_b32_e32 v47, v0
	v_mov_b32_e32 v48, v0
	v_mov_b32_e32 v49, v0
	v_mov_b32_e32 v50, v0
	v_mov_b32_e32 v51, v0
	v_mov_b32_e32 v52, v0
	v_mov_b32_e32 v53, v0
	v_mov_b32_e32 v54, v0
	v_mov_b32_e32 v55, v0
	v_mov_b32_e32 v56, v0
	v_mov_b32_e32 v57, v0
	v_mov_b32_e32 v58, v0
	v_mov_b32_e32 v59, v0
	v_mov_b32_e32 v60, v0
	v_mov_b32_e32 v61, v0
	v_mov_b32_e32 v62, v0
	v_mov_b32_e32 v63, v0
	v_mov_b32_e32 v64, v0
	v_mov_b32_e32 v65, v0
	v_mov_b32_e32 v66, v0
	v_mov_b32_e32 v67, v0
	v_mov_b32_e32 v68, v0
	v_mov_b32_e32 v69, v0
	v_mov_b32_e32 v70, v0
	v_mov_b32_e32 v71, v0
	v_mov_b32_e32 v72, v0
	v_mov_b32_e32 v73, v0
	v_mov_b32_e32 v74, v0
	v_mov_b32_e32 v75, v0
	v_mov_b32_e32 v76, v0
	v_mov_b32_e32 v77, v0
	v_mov_b32_e32 v78, v0
	v_mov_b32_e32 v79, v0
	v_mov_b32_e32 v80, v0
	v_mov_b32_e32 v81, v0
	v_mov_b32_e32 v82, v0
	v_mov_b32_e32 v83, v0
	v_mov_b32_e32 v84, v0
	v_mov_b32_e32 v85, v0
	v_mov_b32_e32 v86, v0
	v_mov_b32_e32 v87, v0
	v_mov_b32_e32 v88, v0
	v_mov_b32_e32 v89, v0
	v_mov_b32_e32 v90, v0
	v_mov_b32_e32 v91, v0
	v_mov_b32_e32 v92, v0
	v_mov_b32_e32 v93, v0
	v_mov_b32_e32 v94, v0
	v_mov_b32_e32 v95, v0
	v_mov_b32_e32 v96, v0
	v_mov_b32_e32 v97, v0
	v_mov_b32_e32 v98, v0
	v_mov_b32_e32 v99, v0
	v_mov_b32_e32 v100, v0
	v_mov_b32_e32 v101, v0
	v_mov_b32_e32 v102, v0
	v_mov_b32_e32 v103, v0
	v_mov_b32_e32 v104, v0
	v_mov_b32_e32 v105, v0
	v_mov_b32_e32 v106, v0
	v_mov_b32_e32 v107, v0
	v_mov_b32_e32 v108, v0
	v_mov_b32_e32 v109, v0
	v_mov_b32_e32 v110, v0
	v_mov_b32_e32 v111, v0
	v_mov_b32_e32 v112, v0
	v_mov_b32_e32 v113, v0
	v_mov_b32_e32 v114, v0
	v_mov_b32_e32 v115, v0
	v_mov_b32_e32 v116, v0
	v_mov_b32_e32 v117, v0
	v_mov_b32_e32 v118, v0
	v_mov_b32_e32 v119, v0
	v_mov_b32_e32 v120, v0
	v_mov_b32_e32 v121, v0
	v_mov_b32_e32 v122, v0
	v_mov_b32_e32 v123, v0
	v_mov_b32_e32 v124, v0
	v_mov_b32_e32 v125, v0
	v_mov_b32_e32 v126, v0
	v_mov_b32_e32 v127, v0
	s_waitcnt vmcnt(16) lgkmcnt(0)
	s_barrier
	v_bfe_u32 v250, v178, 3, 3
	v_and_b32_e32 v251, 7, v178
	v_lshrrev_b32_e32 v252, 1, v250
	v_xor_b32_e32 v251, v251, v252
	v_lshlrev_b32_e32 v251, 4, v251
	v_lshl_or_b32 v250, v250, 11, v251
	v_xor_b32_e32 v251, 64, v250
	v_add_u32_e32 v251, 0x4000, v251
	v_add_u32_e32 v252, 0x8000, v250
	v_add_u32_e32 v253, 0x8000, v251
	v_lshl_add_u64 v[242:243], v[140:141], 0, s[28:29]
	s_mov_b64 s[36:37], 0x80
	v_lshl_add_u64 v[242:243], v[242:243], 0, s[36:37]
	v_lshl_add_u64 v[244:245], v[142:143], 0, s[28:29]
	s_mov_b64 s[36:37], 0x12c00080
	v_lshl_add_u64 v[244:245], v[244:245], 0, s[36:37]
	v_add_u32_e32 v254, v139, v149
	v_add_u32_e32 v255, v153, v149
	v_readfirstlane_b32 s98, v242
	v_readfirstlane_b32 s99, v243
	v_readfirstlane_b32 s100, v244
	v_readfirstlane_b32 s101, v245
	ds_read_b128 v[170:173], v254
	ds_read_b128 v[174:177], v254 offset:2048
	ds_read_b128 v[154:157], v255 offset:32768
	ds_read_b128 v[158:161], v255 offset:34816
	ds_read_b128 v[162:165], v255 offset:36864
	ds_read_b128 v[166:169], v255 offset:38912
	s_nop 4
	s_lshl_b32 m0, s28, 9
	s_and_b32 m0, m0, 0x10000
	s_xor_b32 m0, m0, 0x10000
	s_add_i32 m0, m0, s2
	s_nop 0
	global_load_lds_dwordx4 v250, s[98:99]
	s_add_i32 m0, m0, 0x8000
	s_nop 0
	global_load_lds_dwordx4 v250, s[100:101]
	s_add_i32 m0, m0, 0xffff8400
	s_nop 0
	global_load_lds_dwordx4 v251, s[98:99]
	s_add_i32 m0, m0, 0x8000
	s_nop 0
	global_load_lds_dwordx4 v251, s[100:101]

.LBB0_787:
	v_readfirstlane_b32 s45, v178
	s_lshr_b32 s44, s45, 6
	s_xor_b64 s[50:51], s[8:9], -1
	s_lshl_b32 s10, s44, 5
	s_lshl_b64 s[8:9], s[10:11], 10
	s_lshl_b32 s10, s44, 12
	s_mov_b64 s[48:49], -1
	s_and_b64 vcc, exec, s[50:51]
	s_cbranch_vccz .LBB0_789
	s_add_u32 s37, s56, s42
	s_addc_u32 s51, s57, s43
	s_lshl_b64 s[48:49], s[8:9], 1
	s_add_u32 s50, s37, s48
	s_addc_u32 s51, s51, s49
	s_add_u32 s46, s46, s48
	s_addc_u32 s47, s47, s49
	s_add_i32 s37, s10, 0
	s_mov_b32 m0, s37
	v_mov_b32_e32 v139, v129
	global_load_lds_dwordx4 v128, s[46:47]
	s_add_i32 m0, s37, 0x8000
	v_lshl_add_u64 v[4:5], s[46:47], 0, v[138:139]
	global_load_lds_dwordx4 v128, s[50:51]
	v_lshl_add_u64 v[6:7], v[4:5], 0, s[12:13]
	s_add_i32 m0, s37, 0x400
	v_lshl_add_u64 v[0:1], s[46:47], 0, v[128:129]
	global_load_lds_dwordx4 v[6:7], off
	v_lshl_add_u64 v[6:7], s[50:51], 0, v[138:139]
	v_lshl_add_u64 v[8:9], v[6:7], 0, s[12:13]
	s_add_i32 m0, s37, 0x8400
	v_lshl_add_u64 v[2:3], s[50:51], 0, v[128:129]
	global_load_lds_dwordx4 v[8:9], off
	v_lshl_add_u64 v[0:1], v[0:1], 0, s[14:15]
	s_add_i32 m0, s37, 0x800
	s_or_b32 s51, s10, 0x400
	global_load_lds_dwordx4 v[0:1], off
	v_lshl_add_u64 v[0:1], v[2:3], 0, s[14:15]
	s_add_i32 m0, s37, 0x8800
	s_or_b32 s50, s10, 0x800
	global_load_lds_dwordx4 v[0:1], off
	v_lshl_add_u64 v[0:1], v[4:5], 0, s[16:17]
	s_add_i32 m0, s37, 0xc00
	s_mov_b64 s[48:49], 0
	global_load_lds_dwordx4 v[0:1], off
	v_lshl_add_u64 v[0:1], v[6:7], 0, s[16:17]
	s_add_i32 m0, s37, 0x8c00
	s_or_b32 s37, s10, 0xc00
	global_load_lds_dwordx4 v[0:1], off
	s_waitcnt vmcnt(0)

.LBB0_791:
	s_lshr_b32 s46, s45, 1
	s_and_b32 s46, s46, 0x1ffff80
	v_or_b32_e32 v0, s46, v148
	s_and_b32 s45, s45, 0xc0
	v_lshlrev_b32_e32 v139, 7, v0
	v_or_b32_e32 v0, s45, v148
	s_mov_b32 s45, s11
	s_lshl_b64 s[44:45], s[44:45], 16
	s_add_u32 s40, s44, s40
	s_addc_u32 s41, s45, s41
	s_waitcnt vmcnt(16)
	v_lshlrev_b32_e32 v153, 7, v0
	v_lshl_add_u64 v[0:1], s[38:39], 0, v[130:131]
	s_add_u32 s42, s44, s42
	v_lshl_add_u64 v[140:141], v[0:1], 0, s[40:41]
	s_addc_u32 s43, s45, s43
	v_lshl_add_u64 v[0:1], s[38:39], 0, v[134:135]
	v_mov_b32_e32 v88, 0
	v_lshl_add_u64 v[142:143], v[132:133], 0, s[42:43]
	v_lshl_add_u64 v[144:145], v[0:1], 0, s[40:41]
	v_lshl_add_u64 v[146:147], v[136:137], 0, s[42:43]
	s_mov_b64 s[38:39], 0
	s_mov_b32 s40, 0
	v_mov_b32_e32 v89, v88
	v_mov_b32_e32 v90, v88
	v_mov_b32_e32 v91, v88
	v_mov_b32_e32 v104, v88
	v_mov_b32_e32 v105, v88
	v_mov_b32_e32 v106, v88
	v_mov_b32_e32 v107, v88
	v_mov_b32_e32 v0, v88
	v_mov_b32_e32 v1, v88
	v_mov_b32_e32 v2, v88
	v_mov_b32_e32 v3, v88
	v_mov_b32_e32 v4, v88
	v_mov_b32_e32 v5, v88
	v_mov_b32_e32 v6, v88
	v_mov_b32_e32 v7, v88
	v_mov_b32_e32 v8, v88
	v_mov_b32_e32 v9, v88
	v_mov_b32_e32 v10, v88
	v_mov_b32_e32 v11, v88
	v_mov_b32_e32 v12, v88
	v_mov_b32_e32 v13, v88
	v_mov_b32_e32 v14, v88
	v_mov_b32_e32 v15, v88
	v_mov_b32_e32 v16, v88
	v_mov_b32_e32 v17, v88
	v_mov_b32_e32 v18, v88
	v_mov_b32_e32 v19, v88
	v_mov_b32_e32 v20, v88
	v_mov_b32_e32 v21, v88
	v_mov_b32_e32 v22, v88
	v_mov_b32_e32 v23, v88
	v_mov_b32_e32 v24, v88
	v_mov_b32_e32 v25, v88
	v_mov_b32_e32 v26, v88
	v_mov_b32_e32 v27, v88
	v_mov_b32_e32 v28, v88
	v_mov_b32_e32 v29, v88
	v_mov_b32_e32 v30, v88
	v_mov_b32_e32 v31, v88
	v_mov_b32_e32 v32, v88
	v_mov_b32_e32 v33, v88
	v_mov_b32_e32 v34, v88
	v_mov_b32_e32 v35, v88
	v_mov_b32_e32 v36, v88
	v_mov_b32_e32 v37, v88
	v_mov_b32_e32 v38, v88
	v_mov_b32_e32 v39, v88
	v_mov_b32_e32 v40, v88
	v_mov_b32_e32 v41, v88
	v_mov_b32_e32 v42, v88
	v_mov_b32_e32 v43, v88
	v_mov_b32_e32 v44, v88
	v_mov_b32_e32 v45, v88
	v_mov_b32_e32 v46, v88
	v_mov_b32_e32 v47, v88
	v_mov_b32_e32 v48, v88
	v_mov_b32_e32 v49, v88
	v_mov_b32_e32 v50, v88
	v_mov_b32_e32 v51, v88
	v_mov_b32_e32 v52, v88
	v_mov_b32_e32 v53, v88
	v_mov_b32_e32 v54, v88
	v_mov_b32_e32 v55, v88
	v_mov_b32_e32 v56, v88
	v_mov_b32_e32 v57, v88
	v_mov_b32_e32 v58, v88
	v_mov_b32_e32 v59, v88
	v_mov_b32_e32 v60, v88
	v_mov_b32_e32 v61, v88
	v_mov_b32_e32 v62, v88
	v_mov_b32_e32 v63, v88
	v_mov_b32_e32 v64, v88
	v_mov_b32_e32 v65, v88
	v_mov_b32_e32 v66, v88
	v_mov_b32_e32 v67, v88
	v_mov_b32_e32 v68, v88
	v_mov_b32_e32 v69, v88
	v_mov_b32_e32 v70, v88
	v_mov_b32_e32 v71, v88
	v_mov_b32_e32 v72, v88
	v_mov_b32_e32 v73, v88
	v_mov_b32_e32 v74, v88
	v_mov_b32_e32 v75, v88
	v_mov_b32_e32 v76, v88
	v_mov_b32_e32 v77, v88
	v_mov_b32_e32 v78, v88
	v_mov_b32_e32 v79, v88
	v_mov_b32_e32 v80, v88
	v_mov_b32_e32 v81, v88
	v_mov_b32_e32 v82, v88
	v_mov_b32_e32 v83, v88
	v_mov_b32_e32 v84, v88
	v_mov_b32_e32 v85, v88
	v_mov_b32_e32 v86, v88
	v_mov_b32_e32 v87, v88
	v_mov_b32_e32 v92, v88
	v_mov_b32_e32 v93, v88
	v_mov_b32_e32 v94, v88
	v_mov_b32_e32 v95, v88
	v_mov_b32_e32 v96, v88
	v_mov_b32_e32 v97, v88
	v_mov_b32_e32 v98, v88
	v_mov_b32_e32 v99, v88
	v_mov_b32_e32 v100, v88
	v_mov_b32_e32 v101, v88
	v_mov_b32_e32 v102, v88
	v_mov_b32_e32 v103, v88
	v_mov_b32_e32 v108, v88
	v_mov_b32_e32 v109, v88
	v_mov_b32_e32 v110, v88
	v_mov_b32_e32 v111, v88
	v_mov_b32_e32 v112, v88
	v_mov_b32_e32 v113, v88
	v_mov_b32_e32 v114, v88
	v_mov_b32_e32 v115, v88
	v_mov_b32_e32 v116, v88
	v_mov_b32_e32 v117, v88
	v_mov_b32_e32 v118, v88
	v_mov_b32_e32 v119, v88
	v_mov_b32_e32 v120, v88
	v_mov_b32_e32 v121, v88
	v_mov_b32_e32 v122, v88
	v_mov_b32_e32 v123, v88
	v_mov_b32_e32 v124, v88
	v_mov_b32_e32 v125, v88
	v_mov_b32_e32 v126, v88
	v_mov_b32_e32 v127, v88
	s_waitcnt vmcnt(16) lgkmcnt(0)
	s_barrier
	v_bfe_u32 v250, v178, 3, 3
	v_and_b32_e32 v251, 7, v178
	v_lshrrev_b32_e32 v252, 1, v250
	v_xor_b32_e32 v251, v251, v252
	v_lshlrev_b32_e32 v251, 4, v251
	v_lshl_or_b32 v250, v250, 11, v251
	v_xor_b32_e32 v251, 64, v250
	v_add_u32_e32 v251, 0x4000, v251
	v_add_u32_e32 v252, 0x8000, v250
	v_add_u32_e32 v253, 0x8000, v251
	v_lshl_add_u64 v[242:243], v[140:141], 0, s[38:39]
	s_mov_b64 s[40:41], 0x80
	v_lshl_add_u64 v[242:243], v[242:243], 0, s[40:41]
	v_lshl_add_u64 v[244:245], v[142:143], 0, s[38:39]
	s_mov_b64 s[44:45], 0x12000080
	v_lshl_add_u64 v[244:245], v[244:245], 0, s[44:45]
	v_add_u32_e32 v254, v139, v149
	v_add_u32_e32 v255, v153, v149
	v_readfirstlane_b32 s98, v242
	v_readfirstlane_b32 s99, v243
	v_readfirstlane_b32 s100, v244
	v_readfirstlane_b32 s101, v245
	ds_read_b128 v[162:165], v254
	ds_read_b128 v[166:169], v254 offset:2048
	ds_read_b128 v[154:157], v255 offset:32768
	ds_read_b128 v[158:161], v255 offset:34816
	ds_read_b128 v[170:173], v255 offset:36864
	ds_read_b128 v[174:177], v255 offset:38912
	s_nop 4
	s_lshl_b32 m0, s38, 9
	s_and_b32 m0, m0, 0x10000
	s_xor_b32 m0, m0, 0x10000
	s_add_i32 m0, m0, s10
	s_nop 0
	global_load_lds_dwordx4 v250, s[98:99]
	s_add_i32 m0, m0, 0x8000
	s_nop 0
	global_load_lds_dwordx4 v250, s[100:101]
	s_add_i32 m0, m0, 0xffff8400
	s_nop 0
	global_load_lds_dwordx4 v251, s[98:99]
	s_add_i32 m0, m0, 0x8000
	s_nop 0
	global_load_lds_dwordx4 v251, s[100:101]

.LBB0_1135:
	v_readfirstlane_b32 s47, v178
	s_lshr_b32 s46, s47, 6
	s_xor_b64 s[52:53], s[38:39], -1
	s_lshl_b32 s2, s46, 5
	s_lshl_b64 s[38:39], s[2:3], 10
	s_lshl_b32 s2, s46, 12
	s_mov_b64 s[50:51], -1
	s_and_b64 vcc, exec, s[52:53]
	s_cbranch_vccz .LBB0_1137
	s_add_u32 s29, s59, s44
	s_addc_u32 s53, s60, s45
	s_lshl_b64 s[50:51], s[38:39], 1
	s_add_u32 s52, s29, s50
	s_addc_u32 s53, s53, s51
	s_add_u32 s48, s48, s50
	s_addc_u32 s49, s49, s51
	s_add_i32 s29, s2, 0
	s_mov_b32 m0, s29
	v_mov_b32_e32 v139, v129
	global_load_lds_dwordx4 v128, s[48:49]
	s_add_i32 m0, s29, 0x8000
	v_lshl_add_u64 v[4:5], s[48:49], 0, v[138:139]
	global_load_lds_dwordx4 v128, s[52:53]
	v_lshl_add_u64 v[6:7], v[4:5], 0, s[4:5]
	s_add_i32 m0, s29, 0x400
	v_lshl_add_u64 v[0:1], s[48:49], 0, v[128:129]
	global_load_lds_dwordx4 v[6:7], off
	v_lshl_add_u64 v[6:7], s[52:53], 0, v[138:139]
	v_lshl_add_u64 v[8:9], v[6:7], 0, s[4:5]
	s_add_i32 m0, s29, 0x8400
	v_lshl_add_u64 v[2:3], s[52:53], 0, v[128:129]
	global_load_lds_dwordx4 v[8:9], off
	v_lshl_add_u64 v[0:1], v[0:1], 0, s[6:7]
	s_add_i32 m0, s29, 0x800
	s_or_b32 s53, s2, 0x400
	global_load_lds_dwordx4 v[0:1], off
	v_lshl_add_u64 v[0:1], v[2:3], 0, s[6:7]
	s_add_i32 m0, s29, 0x8800
	s_or_b32 s52, s2, 0x800
	global_load_lds_dwordx4 v[0:1], off
	v_lshl_add_u64 v[0:1], v[4:5], 0, s[8:9]
	s_add_i32 m0, s29, 0xc00
	s_mov_b64 s[50:51], 0
	global_load_lds_dwordx4 v[0:1], off
	v_lshl_add_u64 v[0:1], v[6:7], 0, s[8:9]
	s_add_i32 m0, s29, 0x8c00
	s_or_b32 s29, s2, 0xc00
	global_load_lds_dwordx4 v[0:1], off
	s_waitcnt vmcnt(0)

.LBB0_1139:
	s_lshr_b32 s48, s47, 1
	s_and_b32 s48, s48, 0x1ffff80
	v_or_b32_e32 v0, s48, v148
	s_and_b32 s47, s47, 0xc0
	v_lshlrev_b32_e32 v139, 7, v0
	v_or_b32_e32 v0, s47, v148
	s_mov_b32 s47, s3
	s_lshl_b64 s[46:47], s[46:47], 16
	s_add_u32 s42, s46, s42
	s_addc_u32 s43, s47, s43
	s_waitcnt vmcnt(16)
	v_lshlrev_b32_e32 v153, 7, v0
	v_lshl_add_u64 v[0:1], s[40:41], 0, v[130:131]
	s_add_u32 s44, s46, s44
	v_lshl_add_u64 v[140:141], v[0:1], 0, s[42:43]
	s_addc_u32 s45, s47, s45
	v_lshl_add_u64 v[0:1], s[40:41], 0, v[134:135]
	v_mov_b32_e32 v88, 0
	v_lshl_add_u64 v[142:143], v[132:133], 0, s[44:45]
	v_lshl_add_u64 v[144:145], v[0:1], 0, s[42:43]
	v_lshl_add_u64 v[146:147], v[136:137], 0, s[44:45]
	s_mov_b64 s[40:41], 0
	s_mov_b32 s42, 0
	v_mov_b32_e32 v89, v88
	v_mov_b32_e32 v90, v88
	v_mov_b32_e32 v91, v88
	v_mov_b32_e32 v104, v88
	v_mov_b32_e32 v105, v88
	v_mov_b32_e32 v106, v88
	v_mov_b32_e32 v107, v88
	v_mov_b32_e32 v0, v88
	v_mov_b32_e32 v1, v88
	v_mov_b32_e32 v2, v88
	v_mov_b32_e32 v3, v88
	v_mov_b32_e32 v4, v88
	v_mov_b32_e32 v5, v88
	v_mov_b32_e32 v6, v88
	v_mov_b32_e32 v7, v88
	v_mov_b32_e32 v8, v88
	v_mov_b32_e32 v9, v88
	v_mov_b32_e32 v10, v88
	v_mov_b32_e32 v11, v88
	v_mov_b32_e32 v12, v88
	v_mov_b32_e32 v13, v88
	v_mov_b32_e32 v14, v88
	v_mov_b32_e32 v15, v88
	v_mov_b32_e32 v16, v88
	v_mov_b32_e32 v17, v88
	v_mov_b32_e32 v18, v88
	v_mov_b32_e32 v19, v88
	v_mov_b32_e32 v20, v88
	v_mov_b32_e32 v21, v88
	v_mov_b32_e32 v22, v88
	v_mov_b32_e32 v23, v88
	v_mov_b32_e32 v24, v88
	v_mov_b32_e32 v25, v88
	v_mov_b32_e32 v26, v88
	v_mov_b32_e32 v27, v88
	v_mov_b32_e32 v28, v88
	v_mov_b32_e32 v29, v88
	v_mov_b32_e32 v30, v88
	v_mov_b32_e32 v31, v88
	v_mov_b32_e32 v32, v88
	v_mov_b32_e32 v33, v88
	v_mov_b32_e32 v34, v88
	v_mov_b32_e32 v35, v88
	v_mov_b32_e32 v36, v88
	v_mov_b32_e32 v37, v88
	v_mov_b32_e32 v38, v88
	v_mov_b32_e32 v39, v88
	v_mov_b32_e32 v40, v88
	v_mov_b32_e32 v41, v88
	v_mov_b32_e32 v42, v88
	v_mov_b32_e32 v43, v88
	v_mov_b32_e32 v44, v88
	v_mov_b32_e32 v45, v88
	v_mov_b32_e32 v46, v88
	v_mov_b32_e32 v47, v88
	v_mov_b32_e32 v48, v88
	v_mov_b32_e32 v49, v88
	v_mov_b32_e32 v50, v88
	v_mov_b32_e32 v51, v88
	v_mov_b32_e32 v52, v88
	v_mov_b32_e32 v53, v88
	v_mov_b32_e32 v54, v88
	v_mov_b32_e32 v55, v88
	v_mov_b32_e32 v56, v88
	v_mov_b32_e32 v57, v88
	v_mov_b32_e32 v58, v88
	v_mov_b32_e32 v59, v88
	v_mov_b32_e32 v60, v88
	v_mov_b32_e32 v61, v88
	v_mov_b32_e32 v62, v88
	v_mov_b32_e32 v63, v88
	v_mov_b32_e32 v64, v88
	v_mov_b32_e32 v65, v88
	v_mov_b32_e32 v66, v88
	v_mov_b32_e32 v67, v88
	v_mov_b32_e32 v68, v88
	v_mov_b32_e32 v69, v88
	v_mov_b32_e32 v70, v88
	v_mov_b32_e32 v71, v88
	v_mov_b32_e32 v72, v88
	v_mov_b32_e32 v73, v88
	v_mov_b32_e32 v74, v88
	v_mov_b32_e32 v75, v88
	v_mov_b32_e32 v76, v88
	v_mov_b32_e32 v77, v88
	v_mov_b32_e32 v78, v88
	v_mov_b32_e32 v79, v88
	v_mov_b32_e32 v80, v88
	v_mov_b32_e32 v81, v88
	v_mov_b32_e32 v82, v88
	v_mov_b32_e32 v83, v88
	v_mov_b32_e32 v84, v88
	v_mov_b32_e32 v85, v88
	v_mov_b32_e32 v86, v88
	v_mov_b32_e32 v87, v88
	v_mov_b32_e32 v92, v88
	v_mov_b32_e32 v93, v88
	v_mov_b32_e32 v94, v88
	v_mov_b32_e32 v95, v88
	v_mov_b32_e32 v96, v88
	v_mov_b32_e32 v97, v88
	v_mov_b32_e32 v98, v88
	v_mov_b32_e32 v99, v88
	v_mov_b32_e32 v100, v88
	v_mov_b32_e32 v101, v88
	v_mov_b32_e32 v102, v88
	v_mov_b32_e32 v103, v88
	v_mov_b32_e32 v108, v88
	v_mov_b32_e32 v109, v88
	v_mov_b32_e32 v110, v88
	v_mov_b32_e32 v111, v88
	v_mov_b32_e32 v112, v88
	v_mov_b32_e32 v113, v88
	v_mov_b32_e32 v114, v88
	v_mov_b32_e32 v115, v88
	v_mov_b32_e32 v116, v88
	v_mov_b32_e32 v117, v88
	v_mov_b32_e32 v118, v88
	v_mov_b32_e32 v119, v88
	v_mov_b32_e32 v120, v88
	v_mov_b32_e32 v121, v88
	v_mov_b32_e32 v122, v88
	v_mov_b32_e32 v123, v88
	v_mov_b32_e32 v124, v88
	v_mov_b32_e32 v125, v88
	v_mov_b32_e32 v126, v88
	v_mov_b32_e32 v127, v88
	s_waitcnt vmcnt(16) lgkmcnt(0)
	s_barrier
	v_bfe_u32 v250, v178, 3, 3
	v_and_b32_e32 v251, 7, v178
	v_lshrrev_b32_e32 v252, 1, v250
	v_xor_b32_e32 v251, v251, v252
	v_lshlrev_b32_e32 v251, 4, v251
	v_lshl_or_b32 v250, v250, 11, v251
	v_xor_b32_e32 v251, 64, v250
	v_add_u32_e32 v251, 0x4000, v251
	v_add_u32_e32 v252, 0x8000, v250
	v_add_u32_e32 v253, 0x8000, v251
	v_lshl_add_u64 v[242:243], v[140:141], 0, s[40:41]
	v_lshl_add_u64 v[242:243], v[242:243], 0, s[10:11]
	v_lshl_add_u64 v[244:245], v[142:143], 0, s[40:41]
	v_lshl_add_u64 v[244:245], v[244:245], 0, s[12:13]
	v_add_u32_e32 v254, v139, v149
	v_add_u32_e32 v255, v153, v149
	v_readfirstlane_b32 s98, v242
	v_readfirstlane_b32 s99, v243
	v_readfirstlane_b32 s100, v244
	v_readfirstlane_b32 s101, v245
	ds_read_b128 v[162:165], v254
	ds_read_b128 v[166:169], v254 offset:2048
	ds_read_b128 v[154:157], v255 offset:32768
	ds_read_b128 v[158:161], v255 offset:34816
	ds_read_b128 v[170:173], v255 offset:36864
	ds_read_b128 v[174:177], v255 offset:38912
	s_nop 4
	s_lshl_b32 m0, s40, 9
	s_and_b32 m0, m0, 0x10000
	s_xor_b32 m0, m0, 0x10000
	s_add_i32 m0, m0, s2
	s_nop 0
	global_load_lds_dwordx4 v250, s[98:99]
	s_add_i32 m0, m0, 0x8000
	s_nop 0
	global_load_lds_dwordx4 v250, s[100:101]
	s_add_i32 m0, m0, 0xffff8400
	s_nop 0
	global_load_lds_dwordx4 v251, s[98:99]
	s_add_i32 m0, m0, 0x8000
	s_nop 0
	global_load_lds_dwordx4 v251, s[100:101]

.LBB0_1182:
	v_readfirstlane_b32 s49, v178
	s_lshr_b32 s48, s49, 6
	s_xor_b64 s[64:65], s[40:41], -1
	s_lshl_b32 s2, s48, 5
	s_lshl_b64 s[40:41], s[2:3], 11
	s_lshl_b32 s2, s48, 12
	s_mov_b64 s[52:53], -1
	s_and_b64 vcc, exec, s[64:65]
	s_cbranch_vccz .LBB0_1184
	s_add_u32 s31, s56, s46
	s_addc_u32 s65, s57, s47
	s_lshl_b64 s[52:53], s[40:41], 1
	s_add_u32 s64, s31, s52
	s_addc_u32 s65, s65, s53
	s_add_u32 s50, s50, s52
	s_addc_u32 s51, s51, s53
	s_add_i32 s31, s2, 0
	s_mov_b32 m0, s31
	v_mov_b32_e32 v139, v129
	global_load_lds_dwordx4 v128, s[50:51]
	s_add_i32 m0, s31, 0x8000
	v_lshl_add_u64 v[4:5], s[50:51], 0, v[138:139]
	global_load_lds_dwordx4 v128, s[64:65]
	v_lshl_add_u64 v[6:7], v[4:5], 0, s[6:7]
	s_add_i32 m0, s31, 0x400
	v_lshl_add_u64 v[0:1], s[50:51], 0, v[128:129]
	global_load_lds_dwordx4 v[6:7], off
	v_lshl_add_u64 v[6:7], s[64:65], 0, v[138:139]
	v_lshl_add_u64 v[8:9], v[6:7], 0, s[6:7]
	s_add_i32 m0, s31, 0x8400
	v_lshl_add_u64 v[2:3], s[64:65], 0, v[128:129]
	global_load_lds_dwordx4 v[8:9], off
	v_lshl_add_u64 v[0:1], v[0:1], 0, s[8:9]
	s_add_i32 m0, s31, 0x800
	s_or_b32 s65, s2, 0x400
	global_load_lds_dwordx4 v[0:1], off
	v_lshl_add_u64 v[0:1], v[2:3], 0, s[8:9]
	s_add_i32 m0, s31, 0x8800
	s_or_b32 s64, s2, 0x800
	global_load_lds_dwordx4 v[0:1], off
	v_lshl_add_u64 v[0:1], v[4:5], 0, s[10:11]
	s_add_i32 m0, s31, 0xc00
	s_mov_b64 s[52:53], 0
	global_load_lds_dwordx4 v[0:1], off
	v_lshl_add_u64 v[0:1], v[6:7], 0, s[10:11]
	s_add_i32 m0, s31, 0x8c00
	s_or_b32 s31, s2, 0xc00
	global_load_lds_dwordx4 v[0:1], off
	s_waitcnt vmcnt(0)

.LBB0_1186:
	s_lshr_b32 s50, s49, 1
	s_and_b32 s50, s50, 0x1ffff80
	v_or_b32_e32 v0, s50, v148
	s_and_b32 s49, s49, 0xc0
	v_lshlrev_b32_e32 v139, 7, v0
	v_or_b32_e32 v0, s49, v148
	s_mov_b32 s49, s3
	s_lshl_b64 s[48:49], s[48:49], 17
	s_add_u32 s44, s48, s44
	s_addc_u32 s45, s49, s45
	s_waitcnt vmcnt(16)
	v_lshlrev_b32_e32 v153, 7, v0
	v_lshl_add_u64 v[0:1], s[42:43], 0, v[130:131]
	s_add_u32 s46, s48, s46
	v_lshl_add_u64 v[140:141], v[0:1], 0, s[44:45]
	s_addc_u32 s47, s49, s47
	v_lshl_add_u64 v[0:1], s[42:43], 0, v[134:135]
	v_mov_b32_e32 v88, 0
	v_lshl_add_u64 v[142:143], v[132:133], 0, s[46:47]
	v_lshl_add_u64 v[144:145], v[0:1], 0, s[44:45]
	v_lshl_add_u64 v[146:147], v[136:137], 0, s[46:47]
	s_mov_b64 s[42:43], 0
	s_mov_b32 s44, 0
	v_mov_b32_e32 v89, v88
	v_mov_b32_e32 v90, v88
	v_mov_b32_e32 v91, v88
	v_mov_b32_e32 v104, v88
	v_mov_b32_e32 v105, v88
	v_mov_b32_e32 v106, v88
	v_mov_b32_e32 v107, v88
	v_mov_b32_e32 v0, v88
	v_mov_b32_e32 v1, v88
	v_mov_b32_e32 v2, v88
	v_mov_b32_e32 v3, v88
	v_mov_b32_e32 v4, v88
	v_mov_b32_e32 v5, v88
	v_mov_b32_e32 v6, v88
	v_mov_b32_e32 v7, v88
	v_mov_b32_e32 v8, v88
	v_mov_b32_e32 v9, v88
	v_mov_b32_e32 v10, v88
	v_mov_b32_e32 v11, v88
	v_mov_b32_e32 v12, v88
	v_mov_b32_e32 v13, v88
	v_mov_b32_e32 v14, v88
	v_mov_b32_e32 v15, v88
	v_mov_b32_e32 v16, v88
	v_mov_b32_e32 v17, v88
	v_mov_b32_e32 v18, v88
	v_mov_b32_e32 v19, v88
	v_mov_b32_e32 v20, v88
	v_mov_b32_e32 v21, v88
	v_mov_b32_e32 v22, v88
	v_mov_b32_e32 v23, v88
	v_mov_b32_e32 v24, v88
	v_mov_b32_e32 v25, v88
	v_mov_b32_e32 v26, v88
	v_mov_b32_e32 v27, v88
	v_mov_b32_e32 v28, v88
	v_mov_b32_e32 v29, v88
	v_mov_b32_e32 v30, v88
	v_mov_b32_e32 v31, v88
	v_mov_b32_e32 v32, v88
	v_mov_b32_e32 v33, v88
	v_mov_b32_e32 v34, v88
	v_mov_b32_e32 v35, v88
	v_mov_b32_e32 v36, v88
	v_mov_b32_e32 v37, v88
	v_mov_b32_e32 v38, v88
	v_mov_b32_e32 v39, v88
	v_mov_b32_e32 v40, v88
	v_mov_b32_e32 v41, v88
	v_mov_b32_e32 v42, v88
	v_mov_b32_e32 v43, v88
	v_mov_b32_e32 v44, v88
	v_mov_b32_e32 v45, v88
	v_mov_b32_e32 v46, v88
	v_mov_b32_e32 v47, v88
	v_mov_b32_e32 v48, v88
	v_mov_b32_e32 v49, v88
	v_mov_b32_e32 v50, v88
	v_mov_b32_e32 v51, v88
	v_mov_b32_e32 v52, v88
	v_mov_b32_e32 v53, v88
	v_mov_b32_e32 v54, v88
	v_mov_b32_e32 v55, v88
	v_mov_b32_e32 v56, v88
	v_mov_b32_e32 v57, v88
	v_mov_b32_e32 v58, v88
	v_mov_b32_e32 v59, v88
	v_mov_b32_e32 v60, v88
	v_mov_b32_e32 v61, v88
	v_mov_b32_e32 v62, v88
	v_mov_b32_e32 v63, v88
	v_mov_b32_e32 v64, v88
	v_mov_b32_e32 v65, v88
	v_mov_b32_e32 v66, v88
	v_mov_b32_e32 v67, v88
	v_mov_b32_e32 v68, v88
	v_mov_b32_e32 v69, v88
	v_mov_b32_e32 v70, v88
	v_mov_b32_e32 v71, v88
	v_mov_b32_e32 v72, v88
	v_mov_b32_e32 v73, v88
	v_mov_b32_e32 v74, v88
	v_mov_b32_e32 v75, v88
	v_mov_b32_e32 v76, v88
	v_mov_b32_e32 v77, v88
	v_mov_b32_e32 v78, v88
	v_mov_b32_e32 v79, v88
	v_mov_b32_e32 v80, v88
	v_mov_b32_e32 v81, v88
	v_mov_b32_e32 v82, v88
	v_mov_b32_e32 v83, v88
	v_mov_b32_e32 v84, v88
	v_mov_b32_e32 v85, v88
	v_mov_b32_e32 v86, v88
	v_mov_b32_e32 v87, v88
	v_mov_b32_e32 v92, v88
	v_mov_b32_e32 v93, v88
	v_mov_b32_e32 v94, v88
	v_mov_b32_e32 v95, v88
	v_mov_b32_e32 v96, v88
	v_mov_b32_e32 v97, v88
	v_mov_b32_e32 v98, v88
	v_mov_b32_e32 v99, v88
	v_mov_b32_e32 v100, v88
	v_mov_b32_e32 v101, v88
	v_mov_b32_e32 v102, v88
	v_mov_b32_e32 v103, v88
	v_mov_b32_e32 v108, v88
	v_mov_b32_e32 v109, v88
	v_mov_b32_e32 v110, v88
	v_mov_b32_e32 v111, v88
	v_mov_b32_e32 v112, v88
	v_mov_b32_e32 v113, v88
	v_mov_b32_e32 v114, v88
	v_mov_b32_e32 v115, v88
	v_mov_b32_e32 v116, v88
	v_mov_b32_e32 v117, v88
	v_mov_b32_e32 v118, v88
	v_mov_b32_e32 v119, v88
	v_mov_b32_e32 v120, v88
	v_mov_b32_e32 v121, v88
	v_mov_b32_e32 v122, v88
	v_mov_b32_e32 v123, v88
	v_mov_b32_e32 v124, v88
	v_mov_b32_e32 v125, v88
	v_mov_b32_e32 v126, v88
	v_mov_b32_e32 v127, v88
	s_waitcnt vmcnt(16) lgkmcnt(0)
	s_barrier
	v_bfe_u32 v250, v178, 3, 3
	v_and_b32_e32 v251, 7, v178
	v_lshrrev_b32_e32 v252, 1, v250
	v_xor_b32_e32 v251, v251, v252
	v_lshlrev_b32_e32 v251, 4, v251
	v_lshl_or_b32 v250, v250, 12, v251
	v_xor_b32_e32 v251, 64, v250
	v_add_u32_e32 v251, 0x8000, v251
	v_add_u32_e32 v252, 0x10000, v250
	v_add_u32_e32 v253, 0x10000, v251
	v_lshl_add_u64 v[242:243], v[140:141], 0, s[42:43]
	v_lshl_add_u64 v[242:243], v[242:243], 0, s[12:13]
	v_lshl_add_u64 v[244:245], v[142:143], 0, s[42:43]
	v_lshl_add_u64 v[244:245], v[244:245], 0, s[14:15]
	v_add_u32_e32 v254, v139, v149
	v_add_u32_e32 v255, v153, v149
	v_readfirstlane_b32 s98, v242
	v_readfirstlane_b32 s99, v243
	v_readfirstlane_b32 s100, v244
	v_readfirstlane_b32 s101, v245
	ds_read_b128 v[162:165], v254
	ds_read_b128 v[166:169], v254 offset:2048
	ds_read_b128 v[154:157], v255 offset:32768
	ds_read_b128 v[158:161], v255 offset:34816
	ds_read_b128 v[170:173], v255 offset:36864
	ds_read_b128 v[174:177], v255 offset:38912
	s_nop 4
	s_lshl_b32 m0, s42, 9
	s_and_b32 m0, m0, 0x10000
	s_xor_b32 m0, m0, 0x10000
	s_add_i32 m0, m0, s2
	s_nop 0
	global_load_lds_dwordx4 v250, s[98:99]
	s_add_i32 m0, m0, 0x8000
	s_nop 0
	global_load_lds_dwordx4 v250, s[100:101]
	s_add_i32 m0, m0, 0xffff8400
	s_nop 0
	global_load_lds_dwordx4 v251, s[98:99]
	s_add_i32 m0, m0, 0x8000
	s_nop 0
	global_load_lds_dwordx4 v251, s[100:101]

.LBB0_1238:
	v_readfirstlane_b32 s47, v178
	s_lshr_b32 s46, s47, 6
	s_xor_b64 s[52:53], s[8:9], -1
	s_lshl_b32 s10, s46, 5
	s_lshl_b64 s[8:9], s[10:11], 10
	s_lshl_b32 s10, s46, 12
	s_mov_b64 s[50:51], -1
	s_and_b64 vcc, exec, s[52:53]
	s_cbranch_vccz .LBB0_1240
	s_add_u32 s39, s60, s44
	s_addc_u32 s53, s61, s45
	s_lshl_b64 s[50:51], s[8:9], 1
	s_add_u32 s52, s39, s50
	s_addc_u32 s53, s53, s51
	s_add_u32 s48, s48, s50
	s_addc_u32 s49, s49, s51
	s_add_i32 s39, s10, 0
	s_mov_b32 m0, s39
	v_mov_b32_e32 v141, v129
	global_load_lds_dwordx4 v138, s[48:49]
	s_add_i32 m0, s39, 0x8000
	v_lshl_add_u64 v[4:5], s[48:49], 0, v[140:141]
	global_load_lds_dwordx4 v138, s[52:53]
	v_lshl_add_u64 v[6:7], v[4:5], 0, s[12:13]
	s_add_i32 m0, s39, 0x400
	v_mov_b32_e32 v139, v129
	global_load_lds_dwordx4 v[6:7], off
	v_lshl_add_u64 v[6:7], s[52:53], 0, v[140:141]
	v_lshl_add_u64 v[0:1], s[48:49], 0, v[138:139]
	v_lshl_add_u64 v[8:9], v[6:7], 0, s[12:13]
	s_add_i32 m0, s39, 0x8400
	v_lshl_add_u64 v[2:3], s[52:53], 0, v[138:139]
	global_load_lds_dwordx4 v[8:9], off
	v_lshl_add_u64 v[0:1], v[0:1], 0, s[14:15]
	s_add_i32 m0, s39, 0x800
	s_or_b32 s53, s10, 0x400
	global_load_lds_dwordx4 v[0:1], off
	v_lshl_add_u64 v[0:1], v[2:3], 0, s[14:15]
	s_add_i32 m0, s39, 0x8800
	s_or_b32 s52, s10, 0x800
	global_load_lds_dwordx4 v[0:1], off
	v_lshl_add_u64 v[0:1], v[4:5], 0, s[16:17]
	s_add_i32 m0, s39, 0xc00
	s_mov_b64 s[50:51], 0
	global_load_lds_dwordx4 v[0:1], off
	v_lshl_add_u64 v[0:1], v[6:7], 0, s[16:17]
	s_add_i32 m0, s39, 0x8c00
	s_or_b32 s39, s10, 0xc00
	global_load_lds_dwordx4 v[0:1], off
	s_waitcnt vmcnt(0)

.LBB0_1242:
	s_lshr_b32 s48, s47, 1
	s_and_b32 s48, s48, 0x1ffff80
	v_or_b32_e32 v0, s48, v150
	s_and_b32 s47, s47, 0xc0
	v_lshlrev_b32_e32 v128, 7, v0
	v_or_b32_e32 v0, s47, v150
	s_mov_b32 s47, s11
	s_lshl_b64 s[46:47], s[46:47], 16
	s_add_u32 s42, s46, s42
	s_addc_u32 s43, s47, s43
	s_waitcnt vmcnt(16)
	v_lshlrev_b32_e32 v139, 7, v0
	v_lshl_add_u64 v[0:1], s[40:41], 0, v[130:131]
	s_add_u32 s44, s46, s44
	v_lshl_add_u64 v[142:143], v[0:1], 0, s[42:43]
	s_addc_u32 s45, s47, s45
	v_lshl_add_u64 v[0:1], s[40:41], 0, v[134:135]
	v_mov_b32_e32 v88, 0
	v_lshl_add_u64 v[144:145], v[132:133], 0, s[44:45]
	v_lshl_add_u64 v[146:147], v[0:1], 0, s[42:43]
	v_lshl_add_u64 v[148:149], v[136:137], 0, s[44:45]
	s_mov_b64 s[40:41], 0
	s_mov_b32 s42, 0
	v_mov_b32_e32 v89, v88
	v_mov_b32_e32 v90, v88
	v_mov_b32_e32 v91, v88
	v_mov_b32_e32 v104, v88
	v_mov_b32_e32 v105, v88
	v_mov_b32_e32 v106, v88
	v_mov_b32_e32 v107, v88
	v_mov_b32_e32 v0, v88
	v_mov_b32_e32 v1, v88
	v_mov_b32_e32 v2, v88
	v_mov_b32_e32 v3, v88
	v_mov_b32_e32 v4, v88
	v_mov_b32_e32 v5, v88
	v_mov_b32_e32 v6, v88
	v_mov_b32_e32 v7, v88
	v_mov_b32_e32 v8, v88
	v_mov_b32_e32 v9, v88
	v_mov_b32_e32 v10, v88
	v_mov_b32_e32 v11, v88
	v_mov_b32_e32 v12, v88
	v_mov_b32_e32 v13, v88
	v_mov_b32_e32 v14, v88
	v_mov_b32_e32 v15, v88
	v_mov_b32_e32 v16, v88
	v_mov_b32_e32 v17, v88
	v_mov_b32_e32 v18, v88
	v_mov_b32_e32 v19, v88
	v_mov_b32_e32 v20, v88
	v_mov_b32_e32 v21, v88
	v_mov_b32_e32 v22, v88
	v_mov_b32_e32 v23, v88
	v_mov_b32_e32 v24, v88
	v_mov_b32_e32 v25, v88
	v_mov_b32_e32 v26, v88
	v_mov_b32_e32 v27, v88
	v_mov_b32_e32 v28, v88
	v_mov_b32_e32 v29, v88
	v_mov_b32_e32 v30, v88
	v_mov_b32_e32 v31, v88
	v_mov_b32_e32 v32, v88
	v_mov_b32_e32 v33, v88
	v_mov_b32_e32 v34, v88
	v_mov_b32_e32 v35, v88
	v_mov_b32_e32 v36, v88
	v_mov_b32_e32 v37, v88
	v_mov_b32_e32 v38, v88
	v_mov_b32_e32 v39, v88
	v_mov_b32_e32 v40, v88
	v_mov_b32_e32 v41, v88
	v_mov_b32_e32 v42, v88
	v_mov_b32_e32 v43, v88
	v_mov_b32_e32 v44, v88
	v_mov_b32_e32 v45, v88
	v_mov_b32_e32 v46, v88
	v_mov_b32_e32 v47, v88
	v_mov_b32_e32 v48, v88
	v_mov_b32_e32 v49, v88
	v_mov_b32_e32 v50, v88
	v_mov_b32_e32 v51, v88
	v_mov_b32_e32 v52, v88
	v_mov_b32_e32 v53, v88
	v_mov_b32_e32 v54, v88
	v_mov_b32_e32 v55, v88
	v_mov_b32_e32 v56, v88
	v_mov_b32_e32 v57, v88
	v_mov_b32_e32 v58, v88
	v_mov_b32_e32 v59, v88
	v_mov_b32_e32 v60, v88
	v_mov_b32_e32 v61, v88
	v_mov_b32_e32 v62, v88
	v_mov_b32_e32 v63, v88
	v_mov_b32_e32 v64, v88
	v_mov_b32_e32 v65, v88
	v_mov_b32_e32 v66, v88
	v_mov_b32_e32 v67, v88
	v_mov_b32_e32 v68, v88
	v_mov_b32_e32 v69, v88
	v_mov_b32_e32 v70, v88
	v_mov_b32_e32 v71, v88
	v_mov_b32_e32 v72, v88
	v_mov_b32_e32 v73, v88
	v_mov_b32_e32 v74, v88
	v_mov_b32_e32 v75, v88
	v_mov_b32_e32 v76, v88
	v_mov_b32_e32 v77, v88
	v_mov_b32_e32 v78, v88
	v_mov_b32_e32 v79, v88
	v_mov_b32_e32 v80, v88
	v_mov_b32_e32 v81, v88
	v_mov_b32_e32 v82, v88
	v_mov_b32_e32 v83, v88
	v_mov_b32_e32 v84, v88
	v_mov_b32_e32 v85, v88
	v_mov_b32_e32 v86, v88
	v_mov_b32_e32 v87, v88
	v_mov_b32_e32 v92, v88
	v_mov_b32_e32 v93, v88
	v_mov_b32_e32 v94, v88
	v_mov_b32_e32 v95, v88
	v_mov_b32_e32 v96, v88
	v_mov_b32_e32 v97, v88
	v_mov_b32_e32 v98, v88
	v_mov_b32_e32 v99, v88
	v_mov_b32_e32 v100, v88
	v_mov_b32_e32 v101, v88
	v_mov_b32_e32 v102, v88
	v_mov_b32_e32 v103, v88
	v_mov_b32_e32 v108, v88
	v_mov_b32_e32 v109, v88
	v_mov_b32_e32 v110, v88
	v_mov_b32_e32 v111, v88
	v_mov_b32_e32 v112, v88
	v_mov_b32_e32 v113, v88
	v_mov_b32_e32 v114, v88
	v_mov_b32_e32 v115, v88
	v_mov_b32_e32 v116, v88
	v_mov_b32_e32 v117, v88
	v_mov_b32_e32 v118, v88
	v_mov_b32_e32 v119, v88
	v_mov_b32_e32 v120, v88
	v_mov_b32_e32 v121, v88
	v_mov_b32_e32 v122, v88
	v_mov_b32_e32 v123, v88
	v_mov_b32_e32 v124, v88
	v_mov_b32_e32 v125, v88
	v_mov_b32_e32 v126, v88
	v_mov_b32_e32 v127, v88
	s_waitcnt vmcnt(16) lgkmcnt(0)
	s_barrier
	v_bfe_u32 v250, v178, 3, 3
	v_and_b32_e32 v251, 7, v178
	v_lshrrev_b32_e32 v252, 1, v250
	v_xor_b32_e32 v251, v251, v252
	v_lshlrev_b32_e32 v251, 4, v251
	v_lshl_or_b32 v250, v250, 11, v251
	v_xor_b32_e32 v251, 64, v250
	v_add_u32_e32 v251, 0x4000, v251
	v_add_u32_e32 v252, 0x8000, v250
	v_add_u32_e32 v253, 0x8000, v251
	v_lshl_add_u64 v[242:243], v[142:143], 0, s[40:41]
	v_lshl_add_u64 v[242:243], v[242:243], 0, s[18:19]
	v_lshl_add_u64 v[244:245], v[144:145], 0, s[40:41]
	v_lshl_add_u64 v[244:245], v[244:245], 0, s[20:21]
	v_add_u32_e32 v254, v128, v151
	v_add_u32_e32 v255, v139, v151
	v_readfirstlane_b32 s98, v242
	v_readfirstlane_b32 s99, v243
	v_readfirstlane_b32 s100, v244
	v_readfirstlane_b32 s101, v245
	ds_read_b128 v[164:167], v254
	ds_read_b128 v[168:171], v254 offset:2048
	ds_read_b128 v[156:159], v255 offset:32768
	ds_read_b128 v[160:163], v255 offset:34816
	ds_read_b128 v[172:175], v255 offset:36864
	ds_read_b128 v[188:191], v255 offset:38912
	s_nop 4
	s_lshl_b32 m0, s40, 9
	s_and_b32 m0, m0, 0x10000
	s_xor_b32 m0, m0, 0x10000
	s_add_i32 m0, m0, s10
	s_nop 0
	global_load_lds_dwordx4 v250, s[98:99]
	s_add_i32 m0, m0, 0x8000
	s_nop 0
	global_load_lds_dwordx4 v250, s[100:101]
	s_add_i32 m0, m0, 0xffff8400
	s_nop 0
	global_load_lds_dwordx4 v251, s[98:99]
	s_add_i32 m0, m0, 0x8000
	s_nop 0
	global_load_lds_dwordx4 v251, s[100:101]

.LBB0_1550:
	v_readfirstlane_b32 s47, v178
	s_lshr_b32 s46, s47, 6
	s_xor_b64 s[62:63], s[38:39], -1
	s_lshl_b32 s2, s46, 5
	s_lshl_b64 s[38:39], s[2:3], 10
	s_lshl_b32 s2, s46, 12
	s_mov_b64 s[50:51], -1
	s_and_b64 vcc, exec, s[62:63]
	s_cbranch_vccz .LBB0_1552
	s_add_u32 s29, s54, s44
	s_addc_u32 s63, s55, s45
	s_lshl_b64 s[50:51], s[38:39], 1
	s_add_u32 s62, s29, s50
	s_addc_u32 s63, s63, s51
	s_add_u32 s48, s48, s50
	s_addc_u32 s49, s49, s51
	s_add_i32 s29, s2, 0
	s_mov_b32 m0, s29
	v_mov_b32_e32 v139, v129
	global_load_lds_dwordx4 v128, s[48:49]
	s_add_i32 m0, s29, 0x8000
	v_lshl_add_u64 v[4:5], s[48:49], 0, v[138:139]
	global_load_lds_dwordx4 v128, s[62:63]
	v_lshl_add_u64 v[6:7], v[4:5], 0, s[4:5]
	s_add_i32 m0, s29, 0x400
	v_lshl_add_u64 v[0:1], s[48:49], 0, v[128:129]
	global_load_lds_dwordx4 v[6:7], off
	v_lshl_add_u64 v[6:7], s[62:63], 0, v[138:139]
	v_lshl_add_u64 v[8:9], v[6:7], 0, s[4:5]
	s_add_i32 m0, s29, 0x8400
	v_lshl_add_u64 v[2:3], s[62:63], 0, v[128:129]
	global_load_lds_dwordx4 v[8:9], off
	v_lshl_add_u64 v[0:1], v[0:1], 0, s[6:7]
	s_add_i32 m0, s29, 0x800
	s_or_b32 s63, s2, 0x400
	global_load_lds_dwordx4 v[0:1], off
	v_lshl_add_u64 v[0:1], v[2:3], 0, s[6:7]
	s_add_i32 m0, s29, 0x8800
	s_or_b32 s62, s2, 0x800
	global_load_lds_dwordx4 v[0:1], off
	v_lshl_add_u64 v[0:1], v[4:5], 0, s[8:9]
	s_add_i32 m0, s29, 0xc00
	s_mov_b64 s[50:51], 0
	global_load_lds_dwordx4 v[0:1], off
	v_lshl_add_u64 v[0:1], v[6:7], 0, s[8:9]
	s_add_i32 m0, s29, 0x8c00
	s_or_b32 s29, s2, 0xc00
	global_load_lds_dwordx4 v[0:1], off
	s_waitcnt vmcnt(0)

.LBB0_1609:
	v_readfirstlane_b32 s3, v178
	s_lshr_b32 s2, s3, 6
	s_lshl_b32 s14, s2, 5
	s_lshl_b64 s[0:1], s[14:15], 10
	s_lshl_b32 s6, s2, 12
	s_mov_b64 s[4:5], -1
	s_and_b64 vcc, exec, s[82:83]
	s_cbranch_vccz .LBB0_1611
	s_lshl_b64 s[4:5], s[0:1], 1
	s_add_u32 s8, s80, s4
	s_addc_u32 s9, s81, s5
	s_add_u32 s4, s78, s4
	s_addc_u32 s5, s79, s5
	s_add_i32 s7, s6, 0
	v_mov_b32_e32 v139, v129
	s_mov_b32 m0, s7
	v_mov_b32_e32 v141, v129
	v_lshl_add_u64 v[0:1], s[4:5], 0, v[138:139]
	global_load_lds_dwordx4 v138, s[4:5]
	s_add_i32 m0, s7, 0x8000
	v_lshl_add_u64 v[4:5], s[4:5], 0, v[140:141]
	s_mov_b64 s[4:5], 0x4000
	global_load_lds_dwordx4 v138, s[8:9]
	v_lshl_add_u64 v[6:7], v[4:5], 0, s[4:5]
	s_add_i32 m0, s7, 0x400
	v_lshl_add_u64 v[2:3], s[8:9], 0, v[138:139]
	global_load_lds_dwordx4 v[6:7], off
	v_lshl_add_u64 v[6:7], s[8:9], 0, v[140:141]
	v_lshl_add_u64 v[8:9], v[6:7], 0, s[4:5]
	s_add_i32 m0, s7, 0x8400
	s_mov_b64 s[4:5], 0x8000
	global_load_lds_dwordx4 v[8:9], off
	v_lshl_add_u64 v[0:1], v[0:1], 0, s[4:5]
	s_add_i32 m0, s7, 0x800
	s_or_b32 s9, s6, 0x400
	global_load_lds_dwordx4 v[0:1], off
	v_lshl_add_u64 v[0:1], v[2:3], 0, s[4:5]
	s_add_i32 m0, s7, 0x8800
	s_mov_b64 s[4:5], 0xc000
	global_load_lds_dwordx4 v[0:1], off
	v_lshl_add_u64 v[0:1], v[4:5], 0, s[4:5]
	s_add_i32 m0, s7, 0xc00
	s_or_b32 s8, s6, 0x800
	global_load_lds_dwordx4 v[0:1], off
	v_lshl_add_u64 v[0:1], v[6:7], 0, s[4:5]
	s_add_i32 m0, s7, 0x8c00
	s_or_b32 s7, s6, 0xc00
	global_load_lds_dwordx4 v[0:1], off
	s_waitcnt vmcnt(0)
	s_mov_b64 s[4:5], 0

.LBB0_1613:
	s_lshr_b32 s4, s3, 1
	s_and_b32 s4, s4, 0x1ffff80
	v_or_b32_e32 v0, s4, v154
	s_and_b32 s3, s3, 0xc0
	v_lshlrev_b32_e32 v128, 7, v0
	v_or_b32_e32 v0, s3, v154
	s_mov_b32 s3, s15
	s_lshl_b64 s[2:3], s[2:3], 16
	s_add_u32 s4, s2, s74
	v_lshlrev_b32_e32 v139, 7, v0
	v_lshl_add_u64 v[0:1], s[66:67], 0, v[130:131]
	s_addc_u32 s5, s3, s75
	s_waitcnt vmcnt(16)
	v_lshl_add_u64 v[142:143], v[0:1], 0, s[4:5]
	s_add_u32 s2, s2, s76
	v_lshl_add_u64 v[0:1], s[66:67], 0, v[134:135]
	s_addc_u32 s3, s3, s77
	v_lshl_add_u64 v[146:147], v[0:1], 0, s[4:5]
	v_mov_b32_e32 v0, 0
	v_lshl_add_u64 v[144:145], v[132:133], 0, s[2:3]
	v_lshl_add_u64 v[148:149], v[136:137], 0, s[2:3]
	s_mov_b64 s[2:3], 0
	s_mov_b32 s10, 0
	v_mov_b32_e32 v1, v0
	v_mov_b32_e32 v2, v0
	v_mov_b32_e32 v3, v0
	v_mov_b32_e32 v4, v0
	v_mov_b32_e32 v5, v0
	v_mov_b32_e32 v6, v0
	v_mov_b32_e32 v7, v0
	v_mov_b32_e32 v8, v0
	v_mov_b32_e32 v9, v0
	v_mov_b32_e32 v10, v0
	v_mov_b32_e32 v11, v0
	v_mov_b32_e32 v12, v0
	v_mov_b32_e32 v13, v0
	v_mov_b32_e32 v14, v0
	v_mov_b32_e32 v15, v0
	v_mov_b32_e32 v16, v0
	v_mov_b32_e32 v17, v0
	v_mov_b32_e32 v18, v0
	v_mov_b32_e32 v19, v0
	v_mov_b32_e32 v20, v0
	v_mov_b32_e32 v21, v0
	v_mov_b32_e32 v22, v0
	v_mov_b32_e32 v23, v0
	v_mov_b32_e32 v24, v0
	v_mov_b32_e32 v25, v0
	v_mov_b32_e32 v26, v0
	v_mov_b32_e32 v27, v0
	v_mov_b32_e32 v28, v0
	v_mov_b32_e32 v29, v0
	v_mov_b32_e32 v30, v0
	v_mov_b32_e32 v31, v0
	v_mov_b32_e32 v32, v0
	v_mov_b32_e32 v33, v0
	v_mov_b32_e32 v34, v0
	v_mov_b32_e32 v35, v0
	v_mov_b32_e32 v36, v0
	v_mov_b32_e32 v37, v0
	v_mov_b32_e32 v38, v0
	v_mov_b32_e32 v39, v0
	v_mov_b32_e32 v40, v0
	v_mov_b32_e32 v41, v0
	v_mov_b32_e32 v42, v0
	v_mov_b32_e32 v43, v0
	v_mov_b32_e32 v44, v0
	v_mov_b32_e32 v45, v0
	v_mov_b32_e32 v46, v0
	v_mov_b32_e32 v47, v0
	v_mov_b32_e32 v48, v0
	v_mov_b32_e32 v49, v0
	v_mov_b32_e32 v50, v0
	v_mov_b32_e32 v51, v0
	v_mov_b32_e32 v52, v0
	v_mov_b32_e32 v53, v0
	v_mov_b32_e32 v54, v0
	v_mov_b32_e32 v55, v0
	v_mov_b32_e32 v56, v0
	v_mov_b32_e32 v57, v0
	v_mov_b32_e32 v58, v0
	v_mov_b32_e32 v59, v0
	v_mov_b32_e32 v60, v0
	v_mov_b32_e32 v61, v0
	v_mov_b32_e32 v62, v0
	v_mov_b32_e32 v63, v0
	v_mov_b32_e32 v64, v0
	v_mov_b32_e32 v65, v0
	v_mov_b32_e32 v66, v0
	v_mov_b32_e32 v67, v0
	v_mov_b32_e32 v68, v0
	v_mov_b32_e32 v69, v0
	v_mov_b32_e32 v70, v0
	v_mov_b32_e32 v71, v0
	v_mov_b32_e32 v72, v0
	v_mov_b32_e32 v73, v0
	v_mov_b32_e32 v74, v0
	v_mov_b32_e32 v75, v0
	v_mov_b32_e32 v76, v0
	v_mov_b32_e32 v77, v0
	v_mov_b32_e32 v78, v0
	v_mov_b32_e32 v79, v0
	v_mov_b32_e32 v80, v0
	v_mov_b32_e32 v81, v0
	v_mov_b32_e32 v82, v0
	v_mov_b32_e32 v83, v0
	v_mov_b32_e32 v84, v0
	v_mov_b32_e32 v85, v0
	v_mov_b32_e32 v86, v0
	v_mov_b32_e32 v87, v0
	v_mov_b32_e32 v88, v0
	v_mov_b32_e32 v89, v0
	v_mov_b32_e32 v90, v0
	v_mov_b32_e32 v91, v0
	v_mov_b32_e32 v92, v0
	v_mov_b32_e32 v93, v0
	v_mov_b32_e32 v94, v0
	v_mov_b32_e32 v95, v0
	v_mov_b32_e32 v96, v0
	v_mov_b32_e32 v97, v0
	v_mov_b32_e32 v98, v0
	v_mov_b32_e32 v99, v0
	v_mov_b32_e32 v100, v0
	v_mov_b32_e32 v101, v0
	v_mov_b32_e32 v102, v0
	v_mov_b32_e32 v103, v0
	v_mov_b32_e32 v104, v0
	v_mov_b32_e32 v105, v0
	v_mov_b32_e32 v106, v0
	v_mov_b32_e32 v107, v0
	v_mov_b32_e32 v108, v0
	v_mov_b32_e32 v109, v0
	v_mov_b32_e32 v110, v0
	v_mov_b32_e32 v111, v0
	v_mov_b32_e32 v112, v0
	v_mov_b32_e32 v113, v0
	v_mov_b32_e32 v114, v0
	v_mov_b32_e32 v115, v0
	v_mov_b32_e32 v116, v0
	v_mov_b32_e32 v117, v0
	v_mov_b32_e32 v118, v0
	v_mov_b32_e32 v119, v0
	v_mov_b32_e32 v120, v0
	v_mov_b32_e32 v121, v0
	v_mov_b32_e32 v122, v0
	v_mov_b32_e32 v123, v0
	v_mov_b32_e32 v124, v0
	v_mov_b32_e32 v125, v0
	v_mov_b32_e32 v126, v0
	v_mov_b32_e32 v127, v0
	s_waitcnt vmcnt(16) lgkmcnt(0)
	s_barrier
	v_bfe_u32 v250, v178, 3, 3
	v_and_b32_e32 v251, 7, v178
	v_lshrrev_b32_e32 v252, 1, v250
	v_xor_b32_e32 v251, v251, v252
	v_lshlrev_b32_e32 v251, 4, v251
	v_lshl_or_b32 v250, v250, 11, v251
	v_xor_b32_e32 v251, 64, v250
	v_add_u32_e32 v251, 0x4000, v251
	v_add_u32_e32 v252, 0x8000, v250
	v_add_u32_e32 v253, 0x8000, v251
	v_lshl_add_u64 v[242:243], v[142:143], 0, s[2:3]
	v_lshl_add_u64 v[242:243], v[242:243], 0, s[38:39]
	v_lshl_add_u64 v[244:245], v[144:145], 0, s[2:3]
	v_lshl_add_u64 v[244:245], v[244:245], 0, s[40:41]
	v_add_u32_e32 v254, v128, v155
	v_add_u32_e32 v255, v139, v155
	v_readfirstlane_b32 s98, v242
	v_readfirstlane_b32 s99, v243
	v_readfirstlane_b32 s100, v244
	v_readfirstlane_b32 s101, v245
	ds_read_b128 v[208:211], v254
	ds_read_b128 v[212:215], v254 offset:2048
	ds_read_b128 v[150:153], v255 offset:32768
	ds_read_b128 v[196:199], v255 offset:34816
	ds_read_b128 v[200:203], v255 offset:36864
	ds_read_b128 v[204:207], v255 offset:38912
	s_nop 4
	s_lshl_b32 m0, s2, 9
	s_and_b32 m0, m0, 0x10000
	s_xor_b32 m0, m0, 0x10000
	s_add_i32 m0, m0, s6
	s_nop 0
	global_load_lds_dwordx4 v250, s[98:99]
	s_add_i32 m0, m0, 0x8000
	s_nop 0
	global_load_lds_dwordx4 v250, s[100:101]
	s_add_i32 m0, m0, 0xffff8400
	s_nop 0
	global_load_lds_dwordx4 v251, s[98:99]
	s_add_i32 m0, m0, 0x8000
	s_nop 0
	global_load_lds_dwordx4 v251, s[100:101]

.LBB0_2070:
	s_lshr_b32 s4, s3, 1
	s_and_b32 s4, s4, 0x1ffff80
	v_or_b32_e32 v0, s4, v154
	s_and_b32 s3, s3, 0xc0
	v_lshlrev_b32_e32 v139, 7, v0
	v_or_b32_e32 v0, s3, v154
	s_mov_b32 s3, s15
	s_lshl_b64 s[2:3], s[2:3], 16
	s_add_u32 s4, s2, s74
	s_addc_u32 s5, s3, s75
	s_waitcnt vmcnt(16)
	v_lshlrev_b32_e32 v128, 7, v0
	v_lshl_add_u64 v[0:1], s[66:67], 0, v[130:131]
	s_add_u32 s2, s2, s76
	v_lshl_add_u64 v[142:143], v[0:1], 0, s[4:5]
	s_addc_u32 s3, s3, s77
	v_lshl_add_u64 v[0:1], s[66:67], 0, v[134:135]
	v_mov_b32_e32 v72, 0
	v_lshl_add_u64 v[144:145], v[132:133], 0, s[2:3]
	v_lshl_add_u64 v[146:147], v[0:1], 0, s[4:5]
	v_lshl_add_u64 v[148:149], v[136:137], 0, s[2:3]
	s_mov_b32 s4, 0
	s_mov_b64 s[2:3], 0
	v_mov_b32_e32 v73, v72
	v_mov_b32_e32 v74, v72
	v_mov_b32_e32 v75, v72
	v_mov_b32_e32 v88, v72
	v_mov_b32_e32 v89, v72
	v_mov_b32_e32 v90, v72
	v_mov_b32_e32 v91, v72
	v_mov_b32_e32 v0, v72
	v_mov_b32_e32 v1, v72
	v_mov_b32_e32 v2, v72
	v_mov_b32_e32 v3, v72
	v_mov_b32_e32 v4, v72
	v_mov_b32_e32 v5, v72
	v_mov_b32_e32 v6, v72
	v_mov_b32_e32 v7, v72
	v_mov_b32_e32 v8, v72
	v_mov_b32_e32 v9, v72
	v_mov_b32_e32 v10, v72
	v_mov_b32_e32 v11, v72
	v_mov_b32_e32 v12, v72
	v_mov_b32_e32 v13, v72
	v_mov_b32_e32 v14, v72
	v_mov_b32_e32 v15, v72
	v_mov_b32_e32 v16, v72
	v_mov_b32_e32 v17, v72
	v_mov_b32_e32 v18, v72
	v_mov_b32_e32 v19, v72
	v_mov_b32_e32 v20, v72
	v_mov_b32_e32 v21, v72
	v_mov_b32_e32 v22, v72
	v_mov_b32_e32 v23, v72
	v_mov_b32_e32 v24, v72
	v_mov_b32_e32 v25, v72
	v_mov_b32_e32 v26, v72
	v_mov_b32_e32 v27, v72
	v_mov_b32_e32 v28, v72
	v_mov_b32_e32 v29, v72
	v_mov_b32_e32 v30, v72
	v_mov_b32_e32 v31, v72
	v_mov_b32_e32 v32, v72
	v_mov_b32_e32 v33, v72
	v_mov_b32_e32 v34, v72
	v_mov_b32_e32 v35, v72
	v_mov_b32_e32 v36, v72
	v_mov_b32_e32 v37, v72
	v_mov_b32_e32 v38, v72
	v_mov_b32_e32 v39, v72
	v_mov_b32_e32 v40, v72
	v_mov_b32_e32 v41, v72
	v_mov_b32_e32 v42, v72
	v_mov_b32_e32 v43, v72
	v_mov_b32_e32 v44, v72
	v_mov_b32_e32 v45, v72
	v_mov_b32_e32 v46, v72
	v_mov_b32_e32 v47, v72
	v_mov_b32_e32 v48, v72
	v_mov_b32_e32 v49, v72
	v_mov_b32_e32 v50, v72
	v_mov_b32_e32 v51, v72
	v_mov_b32_e32 v52, v72
	v_mov_b32_e32 v53, v72
	v_mov_b32_e32 v54, v72
	v_mov_b32_e32 v55, v72
	v_mov_b32_e32 v56, v72
	v_mov_b32_e32 v57, v72
	v_mov_b32_e32 v58, v72
	v_mov_b32_e32 v59, v72
	v_mov_b32_e32 v60, v72
	v_mov_b32_e32 v61, v72
	v_mov_b32_e32 v62, v72
	v_mov_b32_e32 v63, v72
	v_mov_b32_e32 v64, v72
	v_mov_b32_e32 v65, v72
	v_mov_b32_e32 v66, v72
	v_mov_b32_e32 v67, v72
	v_mov_b32_e32 v68, v72
	v_mov_b32_e32 v69, v72
	v_mov_b32_e32 v70, v72
	v_mov_b32_e32 v71, v72
	v_mov_b32_e32 v76, v72
	v_mov_b32_e32 v77, v72
	v_mov_b32_e32 v78, v72
	v_mov_b32_e32 v79, v72
	v_mov_b32_e32 v80, v72
	v_mov_b32_e32 v81, v72
	v_mov_b32_e32 v82, v72
	v_mov_b32_e32 v83, v72
	v_mov_b32_e32 v84, v72
	v_mov_b32_e32 v85, v72
	v_mov_b32_e32 v86, v72
	v_mov_b32_e32 v87, v72
	v_mov_b32_e32 v92, v72
	v_mov_b32_e32 v93, v72
	v_mov_b32_e32 v94, v72
	v_mov_b32_e32 v95, v72
	v_mov_b32_e32 v96, v72
	v_mov_b32_e32 v97, v72
	v_mov_b32_e32 v98, v72
	v_mov_b32_e32 v99, v72
	v_mov_b32_e32 v100, v72
	v_mov_b32_e32 v101, v72
	v_mov_b32_e32 v102, v72
	v_mov_b32_e32 v103, v72
	v_mov_b32_e32 v104, v72
	v_mov_b32_e32 v105, v72
	v_mov_b32_e32 v106, v72
	v_mov_b32_e32 v107, v72
	v_mov_b32_e32 v108, v72
	v_mov_b32_e32 v109, v72
	v_mov_b32_e32 v110, v72
	v_mov_b32_e32 v111, v72
	v_mov_b32_e32 v112, v72
	v_mov_b32_e32 v113, v72
	v_mov_b32_e32 v114, v72
	v_mov_b32_e32 v115, v72
	v_mov_b32_e32 v116, v72
	v_mov_b32_e32 v117, v72
	v_mov_b32_e32 v118, v72
	v_mov_b32_e32 v119, v72
	v_mov_b32_e32 v120, v72
	v_mov_b32_e32 v121, v72
	v_mov_b32_e32 v122, v72
	v_mov_b32_e32 v123, v72
	v_mov_b32_e32 v124, v72
	v_mov_b32_e32 v125, v72
	v_mov_b32_e32 v126, v72
	v_mov_b32_e32 v127, v72
	s_waitcnt vmcnt(16) lgkmcnt(0)
	s_barrier
	v_bfe_u32 v250, v178, 3, 3
	v_and_b32_e32 v251, 7, v178
	v_lshrrev_b32_e32 v252, 1, v250
	v_xor_b32_e32 v251, v251, v252
	v_lshlrev_b32_e32 v251, 4, v251
	v_lshl_or_b32 v250, v250, 11, v251
	v_xor_b32_e32 v251, 64, v250
	v_add_u32_e32 v251, 0x4000, v251
	v_add_u32_e32 v252, 0x8000, v250
	v_add_u32_e32 v253, 0x8000, v251
	v_lshl_add_u64 v[242:243], v[142:143], 0, s[2:3]
	v_lshl_add_u64 v[242:243], v[242:243], 0, s[38:39]
	v_lshl_add_u64 v[244:245], v[144:145], 0, s[2:3]
	v_lshl_add_u64 v[244:245], v[244:245], 0, s[40:41]
	v_add_u32_e32 v254, v139, v155
	v_add_u32_e32 v255, v128, v155
	v_readfirstlane_b32 s98, v242
	v_readfirstlane_b32 s99, v243
	v_readfirstlane_b32 s100, v244
	v_readfirstlane_b32 s101, v245
	ds_read_b128 v[150:153], v254
	ds_read_b128 v[204:207], v254 offset:2048
	ds_read_b128 v[196:199], v255 offset:32768
	ds_read_b128 v[200:203], v255 offset:34816
	ds_read_b128 v[208:211], v255 offset:36864
	ds_read_b128 v[212:215], v255 offset:38912
	s_nop 4
	s_lshl_b32 m0, s2, 9
	s_and_b32 m0, m0, 0x10000
	s_xor_b32 m0, m0, 0x10000
	s_add_i32 m0, m0, s6
	s_nop 0
	global_load_lds_dwordx4 v250, s[98:99]
	s_add_i32 m0, m0, 0x8000
	s_nop 0
	global_load_lds_dwordx4 v250, s[100:101]
	s_add_i32 m0, m0, 0xffff8400
	s_nop 0
	global_load_lds_dwordx4 v251, s[98:99]
	s_add_i32 m0, m0, 0x8000
	s_nop 0
	global_load_lds_dwordx4 v251, s[100:101]
